# v78 + attention query-group loop unrolled by hand, Q of group 1 prefetched into v[236:251] during group 0
# baseline (speedup 1.0000x reference)
.LBB0_644:
	s_lshr_b32 s1, s0, 3
	s_and_b32 s1, s1, 24
	v_readlane_b32 s2, v254, 48
	s_add_i32 s6, s1, s2
	s_lshl_b32 s1, s6, 2
	v_readlane_b32 s16, v254, 2
	v_mov_b32_e32 v2, s1
	v_readlane_b32 s28, v254, 14
	v_readlane_b32 s29, v254, 15
	s_lshl_b32 s2, s0, 6
	s_and_b32 s7, s2, 0xfc0
	s_cmpk_gt_u32 s7, 0x7f
	s_cselect_b64 s[2:3], -1, 0
	s_lshl_b32 s15, s0, 4
	global_load_dword v255, v2, s[28:29]
	s_mov_b32 s1, s5
	s_sub_i32 s14, 0x80, s7
	s_lshl_b32 s4, s6, 6
	s_lshl_b32 s0, s6, 7
	s_and_b32 s6, s15, 0xfffff000
	v_readlane_b32 s18, v254, 4
	v_readlane_b32 s19, v254, 5
	s_ashr_i32 s96, s14, 5
	v_lshl_add_u64 v[212:213], v[208:209], 0, s[0:1]
	s_or_b32 s0, s6, s7
	s_mov_b32 s16, 0
	v_lshl_add_u64 v[214:215], v[210:211], 0, s[4:5]
	s_add_i32 s4, s96, -1
	s_add_i32 s97, s96, -3
	v_or_b32_e32 v127, s0, v221
	s_mov_b64 s[18:19], -1
	v_readlane_b32 s17, v254, 3
	v_readlane_b32 s20, v254, 6
	v_readlane_b32 s21, v254, 7
	v_readlane_b32 s22, v254, 8
	v_readlane_b32 s23, v254, 9
	v_readlane_b32 s24, v254, 10
	v_readlane_b32 s25, v254, 11
	v_readlane_b32 s26, v254, 12
	v_readlane_b32 s27, v254, 13
	v_readlane_b32 s30, v254, 16
	v_readlane_b32 s31, v254, 17
	s_mov_b32 s98, 0x20000
	s_mov_b32 s99, 0
.LBB0_645:
	v_lshl_or_b32 v2, s16, 5, v127
	v_ashrrev_i32_e32 v3, 31, v2
	v_lshlrev_b64 v[216:217], 12, v[2:3]
	v_lshl_add_u64 v[6:7], v[212:213], 0, v[216:217]
	global_load_dwordx4 v[2:5], v[6:7], off
	global_load_dwordx4 v[132:135], v[6:7], off offset:32
	global_load_dwordx4 v[136:139], v[6:7], off offset:64
	global_load_dwordx4 v[140:143], v[6:7], off offset:96
	v_lshl_add_u64 v[234:235], v[6:7], 0, s[98:99]
	global_load_dwordx4 v[236:239], v[234:235], off
	global_load_dwordx4 v[240:243], v[234:235], off offset:32
	global_load_dwordx4 v[244:247], v[234:235], off offset:64
	global_load_dwordx4 v[248:251], v[234:235], off offset:96
	s_mul_i32 s7, s16, 0x1200
	s_add_i32 s6, s7, 0x1200
	s_add_i32 s15, s7, 0x2400
	v_add_u32_e32 v18, s7, v222
	v_add_u32_e32 v34, s6, v222
	v_add_u32_e32 v51, s15, v222
	s_add_i32 s14, s7, 0x3600
	ds_read_b128 v[6:9], v18
	ds_read_b128 v[10:13], v18 offset:32
	ds_read_b128 v[14:17], v18 offset:64
	ds_read_b128 v[18:21], v18 offset:96
	ds_read_b128 v[22:25], v34
	ds_read_b128 v[26:29], v34 offset:32
	ds_read_b128 v[30:33], v34 offset:64
	ds_read_b128 v[34:37], v34 offset:96
	s_or_b32 s1, s16, 2
	ds_read_b128 v[38:41], v51
	ds_read_b128 v[42:45], v51 offset:32
	ds_read_b128 v[46:49], v51 offset:64
	ds_read_b128 v[144:147], v51 offset:96
	v_add_u32_e32 v51, s14, v222
	s_or_b32 s20, s16, 4
	s_add_i32 s0, s7, 0x4800
	ds_read_b128 v[148:151], v51
	ds_read_b128 v[152:155], v51 offset:32
	ds_read_b128 v[156:159], v51 offset:64
	ds_read_b128 v[160:163], v51 offset:96
	v_add_u32_e32 v51, s0, v222
	s_cmp_le_i32 s96, s16
	v_cndmask_b32_e64 v50, 0, 1, s[18:19]
	ds_read_b128 v[180:183], v51
	ds_read_b128 v[184:187], v51 offset:32
	ds_read_b128 v[188:191], v51 offset:64
	ds_read_b128 v[192:195], v51 offset:96
	ds_read_b128 v[164:167], v222 offset:27648
	ds_read_b128 v[168:171], v222 offset:27680
	ds_read_b128 v[172:175], v222 offset:27712
	ds_read_b128 v[176:179], v222 offset:27744
	v_mov_b32_e32 v51, v224
	s_cselect_b64 s[18:19], -1, 0
	s_or_b64 s[18:19], s[2:3], s[18:19]
	v_cmp_gt_i32_e32 vcc, 0, v51
	s_and_b64 s[86:87], vcc, s[18:19]
	v_cmp_gt_i32_e32 vcc, 1, v51
	s_and_b64 s[82:83], vcc, s[18:19]
	v_cmp_gt_i32_e32 vcc, 2, v51
	s_and_b64 s[84:85], vcc, s[18:19]
	v_cmp_gt_i32_e32 vcc, 3, v51
	s_and_b64 s[78:79], vcc, s[18:19]
	v_cmp_gt_i32_e32 vcc, 8, v51
	s_and_b64 s[80:81], vcc, s[18:19]
	v_cmp_gt_i32_e32 vcc, 9, v51
	s_and_b64 s[74:75], vcc, s[18:19]
	v_cmp_gt_i32_e32 vcc, 10, v51
	s_and_b64 s[76:77], vcc, s[18:19]
	v_cmp_gt_i32_e32 vcc, 11, v51
	s_and_b64 s[70:71], vcc, s[18:19]
	v_cmp_gt_i32_e32 vcc, 16, v51
	s_and_b64 s[72:73], vcc, s[18:19]
	v_cmp_gt_i32_e32 vcc, 17, v51
	s_and_b64 s[66:67], vcc, s[18:19]
	v_cmp_gt_i32_e32 vcc, 18, v51
	s_and_b64 s[68:69], vcc, s[18:19]
	v_cmp_gt_i32_e32 vcc, 19, v51
	s_and_b64 s[62:63], vcc, s[18:19]
	v_cmp_gt_i32_e32 vcc, 24, v51
	s_and_b64 s[64:65], vcc, s[18:19]
	v_cmp_gt_i32_e32 vcc, 25, v51
	s_and_b64 s[58:59], vcc, s[18:19]
	v_cmp_gt_i32_e32 vcc, 26, v51
	s_and_b64 s[60:61], vcc, s[18:19]
	v_cmp_gt_i32_e32 vcc, 27, v51
	s_and_b64 s[56:57], vcc, s[18:19]
	s_cmp_ge_i32 s16, s4
	s_cselect_b64 s[18:19], -1, 0
	s_or_b64 s[54:55], s[2:3], s[18:19]
	s_cmp_le_i32 s96, s1
	s_cselect_b64 s[18:19], -1, 0
	s_or_b64 s[52:53], s[2:3], s[18:19]
	s_cmp_ge_i32 s16, s97
	s_cselect_b64 s[16:17], -1, 0
	s_or_b64 s[36:37], s[2:3], s[16:17]
	s_cmp_le_i32 s96, s20
	s_cselect_b64 s[16:17], -1, 0
	s_or_b64 s[16:17], s[2:3], s[16:17]
	v_cmp_lt_i32_e32 vcc, -1, v51
	s_and_b64 s[50:51], vcc, s[16:17]
	v_cmp_lt_i32_e32 vcc, 0, v51
	s_and_b64 s[46:47], vcc, s[16:17]
	v_cmp_lt_i32_e32 vcc, 1, v51
	s_and_b64 s[48:49], vcc, s[16:17]
	v_cmp_lt_i32_e32 vcc, 2, v51
	s_and_b64 s[42:43], vcc, s[16:17]
	v_cmp_lt_i32_e32 vcc, 7, v51
	s_and_b64 s[44:45], vcc, s[16:17]
	v_cmp_lt_i32_e32 vcc, 8, v51
	s_and_b64 s[38:39], vcc, s[16:17]
	v_cmp_lt_i32_e32 vcc, 9, v51
	s_and_b64 s[40:41], vcc, s[16:17]
	v_cmp_lt_i32_e32 vcc, 10, v51
	s_and_b64 s[30:31], vcc, s[16:17]
	v_cmp_lt_i32_e32 vcc, 15, v51
	s_waitcnt vmcnt(7) lgkmcnt(14)
	v_mul_f32_e32 v201, 0x3fb8aa3b, v255
	v_mfma_f32_32x32x16_bf16 v[82:97], v[6:9], v[2:5], 0
	s_and_b64 s[34:35], vcc, s[16:17]
	v_cmp_lt_i32_e32 vcc, 16, v51
	s_and_b64 s[26:27], vcc, s[16:17]
	v_cmp_lt_i32_e32 vcc, 17, v51
	s_and_b64 s[28:29], vcc, s[16:17]
	v_cmp_lt_i32_e32 vcc, 18, v51
	s_and_b64 s[22:23], vcc, s[16:17]
	v_mfma_f32_32x32x16_bf16 v[66:81], v[22:25], v[2:5], 0
	v_cmp_lt_i32_e32 vcc, 23, v51
	s_and_b64 s[24:25], vcc, s[16:17]
	v_cmp_lt_i32_e32 vcc, 24, v51
	s_and_b64 s[18:19], vcc, s[16:17]
	v_cmp_lt_i32_e32 vcc, 25, v51
	s_and_b64 s[20:21], vcc, s[16:17]
	v_cmp_lt_i32_e32 vcc, 26, v51
	s_and_b64 vcc, vcc, s[16:17]
	v_cmp_ne_u32_e64 s[16:17], 1, v50
	s_waitcnt vmcnt(6)
	v_mfma_f32_32x32x16_bf16 v[82:97], v[10:13], v[132:135], v[82:97]
	s_mov_b32 s1, 0xf149f2ca
	v_mfma_f32_32x32x16_bf16 v[66:81], v[26:29], v[132:135], v[66:81]
	v_mfma_f32_32x32x16_bf16 v[50:65], v[38:41], v[2:5], 0
	s_waitcnt vmcnt(5)
	v_mfma_f32_32x32x16_bf16 v[82:97], v[14:17], v[136:139], v[82:97]
	v_mfma_f32_32x32x16_bf16 v[66:81], v[30:33], v[136:139], v[66:81]
	v_mfma_f32_32x32x16_bf16 v[50:65], v[42:45], v[132:135], v[50:65]
	s_waitcnt vmcnt(4)
	v_mfma_f32_32x32x16_bf16 v[82:97], v[18:21], v[140:143], v[82:97]
	v_mfma_f32_32x32x16_bf16 v[66:81], v[34:37], v[140:143], v[66:81]
	s_waitcnt lgkmcnt(13)
	v_mfma_f32_32x32x16_bf16 v[50:65], v[46:49], v[136:139], v[50:65]
	s_waitcnt lgkmcnt(11)
	v_mfma_f32_32x32x16_bf16 v[34:49], v[148:151], v[2:5], 0
	s_waitcnt lgkmcnt(7)
	v_mfma_f32_32x32x16_bf16 v[18:33], v[180:183], v[2:5], 0
	s_waitcnt lgkmcnt(3)
	v_mfma_f32_32x32x16_bf16 v[2:17], v[164:167], v[2:5], 0
	s_waitcnt lgkmcnt(2)
	v_mfma_f32_32x32x16_bf16 v[2:17], v[168:171], v[132:135], v[2:17]
	v_mfma_f32_32x32x16_bf16 v[34:49], v[152:155], v[132:135], v[34:49]
	v_mfma_f32_32x32x16_bf16 v[18:33], v[184:187], v[132:135], v[18:33]
	s_waitcnt lgkmcnt(1)
	v_mfma_f32_32x32x16_bf16 v[2:17], v[172:175], v[136:139], v[2:17]
	v_mfma_f32_32x32x16_bf16 v[34:49], v[156:159], v[136:139], v[34:49]
	v_mfma_f32_32x32x16_bf16 v[18:33], v[188:191], v[136:139], v[18:33]
	s_waitcnt lgkmcnt(0)
	v_mfma_f32_32x32x16_bf16 v[2:17], v[176:179], v[140:143], v[2:17]
	v_mfma_f32_32x32x16_bf16 v[50:65], v[144:147], v[140:143], v[50:65]
	s_nop 10
	v_mul_f32_e32 v12, 0x3fb8aa3b, v83
	v_cndmask_b32_e64 v144, v226, v12, s[82:83]
	v_mul_f32_e32 v12, 0x3fb8aa3b, v84
	v_mul_f32_e32 v10, 0x3fb8aa3b, v82
	v_cndmask_b32_e64 v10, v226, v10, s[86:87]
	v_max_f32_e32 v11, v201, v201
	v_max_f32_e32 v11, v11, v10
	v_mfma_f32_32x32x16_bf16 v[34:49], v[160:163], v[140:143], v[34:49]
	v_mfma_f32_32x32x16_bf16 v[18:33], v[192:195], v[140:143], v[18:33]
	v_cndmask_b32_e64 v142, v226, v12, s[84:85]
	v_mul_f32_e32 v12, 0x3fb8aa3b, v85
	v_cndmask_b32_e64 v143, v226, v12, s[78:79]
	v_mul_f32_e32 v12, 0x3fb8aa3b, v86
	v_cndmask_b32_e64 v140, v226, v12, s[80:81]
	v_mul_f32_e32 v12, 0x3fb8aa3b, v87
	v_cndmask_b32_e64 v141, v226, v12, s[74:75]
	v_mul_f32_e32 v12, 0x3fb8aa3b, v88
	v_cndmask_b32_e64 v138, v226, v12, s[76:77]
	v_mul_f32_e32 v12, 0x3fb8aa3b, v89
	v_cndmask_b32_e64 v139, v226, v12, s[70:71]
	v_mul_f32_e32 v12, 0x3fb8aa3b, v90
	v_cndmask_b32_e64 v136, v226, v12, s[72:73]
	v_mul_f32_e32 v12, 0x3fb8aa3b, v91
	v_max3_f32 v11, v11, v144, v142
	v_cndmask_b32_e64 v137, v226, v12, s[66:67]
	v_mul_f32_e32 v12, 0x3fb8aa3b, v92
	v_max3_f32 v11, v11, v143, v140
	v_cndmask_b32_e64 v134, v226, v12, s[68:69]
	v_mul_f32_e32 v12, 0x3fb8aa3b, v93
	v_max3_f32 v11, v11, v141, v138
	v_cndmask_b32_e64 v135, v226, v12, s[62:63]
	v_mul_f32_e32 v12, 0x3fb8aa3b, v94
	v_max3_f32 v11, v11, v139, v136
	v_cndmask_b32_e64 v132, v226, v12, s[64:65]
	v_mul_f32_e32 v12, 0x3fb8aa3b, v95
	v_max3_f32 v11, v11, v137, v134
	v_cndmask_b32_e64 v133, v226, v12, s[58:59]
	v_mul_f32_e32 v12, 0x3fb8aa3b, v96
	v_max3_f32 v11, v11, v135, v132
	v_cndmask_b32_e64 v95, v226, v12, s[60:61]
	v_max3_f32 v145, v11, v133, v95
	v_mul_f32_e32 v11, 0x3fb8aa3b, v97
	v_cndmask_b32_e64 v96, v226, v11, s[56:57]
	v_mul_f32_e32 v11, 0x3fb8aa3b, v66
	v_cndmask_b32_e64 v94, v226, v11, s[54:55]
	v_mul_f32_e32 v11, 0x3fb8aa3b, v67
	v_cndmask_b32_e64 v93, v226, v11, s[54:55]
	v_mul_f32_e32 v11, 0x3fb8aa3b, v68
	v_cndmask_b32_e64 v92, v226, v11, s[54:55]
	v_mul_f32_e32 v11, 0x3fb8aa3b, v69
	v_cndmask_b32_e64 v91, v226, v11, s[54:55]
	v_mul_f32_e32 v11, 0x3fb8aa3b, v70
	v_cndmask_b32_e64 v90, v226, v11, s[54:55]
	v_mul_f32_e32 v11, 0x3fb8aa3b, v71
	v_cndmask_b32_e64 v89, v226, v11, s[54:55]
	v_mul_f32_e32 v11, 0x3fb8aa3b, v72
	v_cndmask_b32_e64 v88, v226, v11, s[54:55]
	v_mul_f32_e32 v11, 0x3fb8aa3b, v73
	v_cndmask_b32_e64 v87, v226, v11, s[54:55]
	v_mul_f32_e32 v11, 0x3fb8aa3b, v74
	v_cndmask_b32_e64 v86, v226, v11, s[54:55]
	v_mul_f32_e32 v11, 0x3fb8aa3b, v75
	v_cndmask_b32_e64 v85, v226, v11, s[54:55]
	v_mul_f32_e32 v11, 0x3fb8aa3b, v76
	v_cndmask_b32_e64 v84, v226, v11, s[54:55]
	v_mul_f32_e32 v11, 0x3fb8aa3b, v77
	v_cndmask_b32_e64 v83, v226, v11, s[54:55]
	v_mul_f32_e32 v11, 0x3fb8aa3b, v78
	v_cndmask_b32_e64 v82, v226, v11, s[54:55]
	v_mul_f32_e32 v11, 0x3fb8aa3b, v79
	v_cndmask_b32_e64 v78, v226, v11, s[54:55]
	v_mul_f32_e32 v11, 0x3fb8aa3b, v80
	v_cndmask_b32_e64 v77, v226, v11, s[54:55]
	v_mul_f32_e32 v11, 0x3fb8aa3b, v81
	v_cndmask_b32_e64 v76, v226, v11, s[54:55]
	v_mul_f32_e32 v11, 0x3fb8aa3b, v50
	v_cndmask_b32_e64 v75, v226, v11, s[52:53]
	v_mul_f32_e32 v11, 0x3fb8aa3b, v51
	v_cndmask_b32_e64 v74, v226, v11, s[52:53]
	v_mul_f32_e32 v11, 0x3fb8aa3b, v52
	v_cndmask_b32_e64 v73, v226, v11, s[52:53]
	v_mul_f32_e32 v11, 0x3fb8aa3b, v53
	v_cndmask_b32_e64 v72, v226, v11, s[52:53]
	v_mul_f32_e32 v11, 0x3fb8aa3b, v54
	v_cndmask_b32_e64 v71, v226, v11, s[52:53]
	v_mul_f32_e32 v11, 0x3fb8aa3b, v55
	v_cndmask_b32_e64 v70, v226, v11, s[52:53]
	v_mul_f32_e32 v11, 0x3fb8aa3b, v56
	v_cndmask_b32_e64 v69, v226, v11, s[52:53]
	v_mul_f32_e32 v11, 0x3fb8aa3b, v57
	v_cndmask_b32_e64 v68, v226, v11, s[52:53]
	v_mul_f32_e32 v11, 0x3fb8aa3b, v58
	v_cndmask_b32_e64 v67, v226, v11, s[52:53]
	v_mul_f32_e32 v11, 0x3fb8aa3b, v59
	v_cndmask_b32_e64 v66, v226, v11, s[52:53]
	v_mul_f32_e32 v11, 0x3fb8aa3b, v60
	v_cndmask_b32_e64 v59, v226, v11, s[52:53]
	v_mul_f32_e32 v11, 0x3fb8aa3b, v61
	v_cndmask_b32_e64 v58, v226, v11, s[52:53]
	v_mul_f32_e32 v11, 0x3fb8aa3b, v62
	v_cndmask_b32_e64 v57, v226, v11, s[52:53]
	v_mul_f32_e32 v11, 0x3fb8aa3b, v63
	v_cndmask_b32_e64 v56, v226, v11, s[52:53]
	v_mul_f32_e32 v11, 0x3fb8aa3b, v64
	v_cndmask_b32_e64 v55, v226, v11, s[52:53]
	v_mul_f32_e32 v11, 0x3fb8aa3b, v65
	v_cndmask_b32_e64 v54, v226, v11, s[52:53]
	v_mul_f32_e32 v11, 0x3fb8aa3b, v34
	v_cndmask_b32_e64 v53, v226, v11, s[36:37]
	v_mul_f32_e32 v11, 0x3fb8aa3b, v35
	v_cndmask_b32_e64 v52, v226, v11, s[36:37]
	v_mul_f32_e32 v11, 0x3fb8aa3b, v36
	v_cndmask_b32_e64 v51, v226, v11, s[36:37]
	v_mul_f32_e32 v11, 0x3fb8aa3b, v37
	v_cndmask_b32_e64 v50, v226, v11, s[36:37]
	v_mul_f32_e32 v11, 0x3fb8aa3b, v38
	v_max3_f32 v38, v145, v96, v94
	v_max3_f32 v38, v38, v93, v92
	v_max3_f32 v38, v38, v91, v90
	v_max3_f32 v38, v38, v89, v88
	v_max3_f32 v38, v38, v87, v86
	v_max3_f32 v38, v38, v85, v84
	v_max3_f32 v38, v38, v83, v82
	v_max3_f32 v38, v38, v78, v77
	v_max3_f32 v38, v38, v76, v75
	v_max3_f32 v38, v38, v74, v73
	v_max3_f32 v38, v38, v72, v71
	v_max3_f32 v38, v38, v70, v69
	v_cndmask_b32_e64 v37, v226, v11, s[36:37]
	v_mul_f32_e32 v11, 0x3fb8aa3b, v39
	v_max3_f32 v38, v38, v68, v67
	v_cndmask_b32_e64 v36, v226, v11, s[36:37]
	v_mul_f32_e32 v11, 0x3fb8aa3b, v40
	v_max3_f32 v38, v38, v66, v59
	v_cndmask_b32_e64 v35, v226, v11, s[36:37]
	v_mul_f32_e32 v11, 0x3fb8aa3b, v41
	v_max3_f32 v38, v38, v58, v57
	v_cndmask_b32_e64 v34, v226, v11, s[36:37]
	v_mul_f32_e32 v11, 0x3fb8aa3b, v42
	v_max3_f32 v38, v38, v56, v55
	v_cndmask_b32_e64 v17, v226, v11, s[36:37]
	v_mul_f32_e32 v11, 0x3fb8aa3b, v43
	v_max3_f32 v38, v38, v54, v53
	v_cndmask_b32_e64 v16, v226, v11, s[36:37]
	v_mul_f32_e32 v11, 0x3fb8aa3b, v44
	v_max3_f32 v38, v38, v52, v51
	v_cndmask_b32_e64 v15, v226, v11, s[36:37]
	v_mul_f32_e32 v11, 0x3fb8aa3b, v45
	v_max3_f32 v38, v38, v50, v37
	v_mul_f32_e32 v19, 0x3fb8aa3b, v19
	v_cndmask_b32_e64 v14, v226, v11, s[36:37]
	v_mul_f32_e32 v11, 0x3fb8aa3b, v46
	v_max3_f32 v38, v38, v36, v35
	v_cndmask_b32_e64 v45, v226, v19, s[46:47]
	v_mul_f32_e32 v19, 0x3fb8aa3b, v20
	v_cndmask_b32_e64 v13, v226, v11, s[36:37]
	v_mul_f32_e32 v11, 0x3fb8aa3b, v47
	v_max3_f32 v38, v38, v34, v17
	v_cndmask_b32_e64 v42, v226, v19, s[48:49]
	v_mul_f32_e32 v19, 0x3fb8aa3b, v21
	v_cndmask_b32_e64 v12, v226, v11, s[36:37]
	v_mul_f32_e32 v11, 0x3fb8aa3b, v48
	v_max3_f32 v38, v38, v16, v15
	v_cndmask_b32_e64 v43, v226, v19, s[42:43]
	v_mul_f32_e32 v19, 0x3fb8aa3b, v22
	v_cndmask_b32_e64 v11, v226, v11, s[36:37]
	v_max3_f32 v38, v38, v14, v13
	v_mul_f32_e32 v39, 0x3fb8aa3b, v49
	v_mul_f32_e32 v18, 0x3fb8aa3b, v18
	v_cndmask_b32_e64 v40, v226, v19, s[44:45]
	v_mul_f32_e32 v19, 0x3fb8aa3b, v23
	v_max3_f32 v38, v38, v12, v11
	v_cndmask_b32_e64 v46, v226, v39, s[36:37]
	v_cndmask_b32_e64 v44, v226, v18, s[50:51]
	v_cndmask_b32_e64 v41, v226, v19, s[38:39]
	v_mul_f32_e32 v19, 0x3fb8aa3b, v24
	v_max3_f32 v18, v38, v46, v44
	v_cndmask_b32_e64 v38, v226, v19, s[40:41]
	v_mul_f32_e32 v19, 0x3fb8aa3b, v25
	v_cndmask_b32_e64 v39, v226, v19, s[30:31]
	v_mul_f32_e32 v19, 0x3fb8aa3b, v26
	v_max3_f32 v18, v18, v45, v42
	v_cndmask_b32_e64 v24, v226, v19, s[34:35]
	v_mul_f32_e32 v19, 0x3fb8aa3b, v27
	v_max3_f32 v18, v18, v43, v40
	v_cndmask_b32_e64 v25, v226, v19, s[26:27]
	v_mul_f32_e32 v19, 0x3fb8aa3b, v28
	v_max3_f32 v18, v18, v41, v38
	v_cndmask_b32_e64 v22, v226, v19, s[28:29]
	v_mul_f32_e32 v19, 0x3fb8aa3b, v29
	v_max3_f32 v18, v18, v39, v24
	v_cndmask_b32_e64 v23, v226, v19, s[22:23]
	v_mul_f32_e32 v19, 0x3fb8aa3b, v30
	v_max3_f32 v18, v18, v25, v22
	v_cndmask_b32_e64 v20, v226, v19, s[24:25]
	v_max3_f32 v19, v18, v23, v20
	v_mul_f32_e32 v18, 0x3fb8aa3b, v31
	v_cndmask_b32_e64 v21, v226, v18, s[18:19]
	v_mul_f32_e32 v18, 0x3fb8aa3b, v32
	v_cndmask_b32_e64 v18, v226, v18, s[20:21]
	v_max3_f32 v26, v19, v21, v18
	v_mul_f32_e32 v19, 0x3fb8aa3b, v33
	v_cndmask_b32_e32 v19, v226, v19, vcc
	v_mul_f32_e32 v27, 0x3fb8aa3b, v2
	v_max3_f32 v26, v26, v19, v27
	v_mul_f32_e32 v27, 0x3fb8aa3b, v3
	v_mul_f32_e32 v28, 0x3fb8aa3b, v4
	v_max3_f32 v26, v26, v27, v28
	v_mul_f32_e32 v27, 0x3fb8aa3b, v5
	v_mul_f32_e32 v28, 0x3fb8aa3b, v6
	v_max3_f32 v26, v26, v27, v28
	v_mul_f32_e32 v27, 0x3fb8aa3b, v7
	v_mul_f32_e32 v28, 0x3fb8aa3b, v8
	v_max3_f32 v26, v26, v27, v28
	v_mul_f32_e32 v27, 0x3fb8aa3b, v9
	v_and_b32_e32 v28, 64, v232
	v_max3_f32 v26, v26, v27, s1
	v_xor_b32_e32 v27, 32, v232
	v_add_u32_e32 v28, 64, v28
	v_cmp_lt_i32_e32 vcc, v27, v28
	s_mov_b64 s[18:19], 0
	s_nop 0
	v_cndmask_b32_e32 v27, v232, v27, vcc
	v_lshlrev_b32_e32 v27, 2, v27
	ds_bpermute_b32 v28, v27, v26
	s_waitcnt lgkmcnt(0)
	v_max_f32_e32 v28, v28, v28
	v_max_f32_e32 v26, v26, v28
	v_sub_f32_e32 v10, v10, v26
	v_exp_f32_e32 v10, v10
	v_sub_f32_e32 v29, v144, v26
	v_exp_f32_e32 v29, v29
	v_sub_f32_e32 v30, v142, v26
	v_exp_f32_e32 v30, v30
	v_sub_f32_e32 v31, v143, v26
	v_exp_f32_e32 v31, v31
	v_sub_f32_e32 v32, v140, v26
	v_add_f32_e32 v28, 0, v10
	v_exp_f32_e32 v32, v32
	v_sub_f32_e32 v33, v141, v26
	v_add_f32_e32 v28, v28, v29
	v_exp_f32_e32 v33, v33
	v_sub_f32_e32 v47, v138, v26
	v_add_f32_e32 v28, v28, v30
	v_exp_f32_e32 v47, v47
	v_sub_f32_e32 v48, v139, v26
	v_add_f32_e32 v28, v28, v31
	v_exp_f32_e32 v48, v48
	v_sub_f32_e32 v49, v136, v26
	v_add_f32_e32 v28, v28, v32
	v_exp_f32_e32 v49, v49
	v_sub_f32_e32 v60, v137, v26
	v_add_f32_e32 v28, v28, v33
	v_exp_f32_e32 v60, v60
	v_sub_f32_e32 v61, v134, v26
	v_add_f32_e32 v28, v28, v47
	v_exp_f32_e32 v61, v61
	v_sub_f32_e32 v62, v135, v26
	v_add_f32_e32 v28, v28, v48
	v_exp_f32_e32 v62, v62
	v_sub_f32_e32 v63, v132, v26
	v_add_f32_e32 v28, v28, v49
	v_exp_f32_e32 v63, v63
	v_sub_f32_e32 v64, v133, v26
	v_add_f32_e32 v28, v28, v60
	v_exp_f32_e32 v64, v64
	v_sub_f32_e32 v65, v95, v26
	v_add_f32_e32 v28, v28, v61
	v_exp_f32_e32 v65, v65
	v_sub_f32_e32 v79, v96, v26
	v_add_f32_e32 v28, v28, v62
	v_exp_f32_e32 v79, v79
	v_sub_f32_e32 v80, v94, v26
	v_add_f32_e32 v28, v28, v63
	v_exp_f32_e32 v80, v80
	v_sub_f32_e32 v81, v93, v26
	v_add_f32_e32 v28, v28, v64
	v_exp_f32_e32 v81, v81
	v_sub_f32_e32 v92, v92, v26
	v_add_f32_e32 v28, v28, v65
	v_exp_f32_e32 v92, v92
	v_sub_f32_e32 v91, v91, v26
	v_add_f32_e32 v28, v28, v79
	v_exp_f32_e32 v91, v91
	v_sub_f32_e32 v90, v90, v26
	v_add_f32_e32 v28, v28, v80
	v_exp_f32_e32 v90, v90
	v_sub_f32_e32 v89, v89, v26
	v_add_f32_e32 v28, v28, v81
	v_exp_f32_e32 v89, v89
	v_sub_f32_e32 v88, v88, v26
	v_add_f32_e32 v28, v28, v92
	v_exp_f32_e32 v88, v88
	v_sub_f32_e32 v87, v87, v26
	v_add_f32_e32 v28, v28, v91
	v_exp_f32_e32 v87, v87
	v_sub_f32_e32 v86, v86, v26
	v_add_f32_e32 v28, v28, v90
	v_exp_f32_e32 v86, v86
	v_sub_f32_e32 v85, v85, v26
	v_add_f32_e32 v28, v28, v89
	v_exp_f32_e32 v85, v85
	v_sub_f32_e32 v84, v84, v26
	v_add_f32_e32 v28, v28, v88
	v_exp_f32_e32 v84, v84
	v_sub_f32_e32 v83, v83, v26
	v_add_f32_e32 v28, v28, v87
	v_exp_f32_e32 v83, v83
	v_sub_f32_e32 v82, v82, v26
	v_add_f32_e32 v28, v28, v86
	v_exp_f32_e32 v82, v82
	v_sub_f32_e32 v78, v78, v26
	v_add_f32_e32 v28, v28, v85
	v_exp_f32_e32 v78, v78
	v_sub_f32_e32 v77, v77, v26
	v_add_f32_e32 v28, v28, v84
	v_exp_f32_e32 v77, v77
	v_sub_f32_e32 v76, v76, v26
	v_add_f32_e32 v28, v28, v83
	v_exp_f32_e32 v76, v76
	v_sub_f32_e32 v75, v75, v26
	v_add_f32_e32 v28, v28, v82
	v_exp_f32_e32 v75, v75
	v_sub_f32_e32 v74, v74, v26
	v_add_f32_e32 v28, v28, v78
	v_exp_f32_e32 v74, v74
	v_sub_f32_e32 v73, v73, v26
	v_add_f32_e32 v28, v28, v77
	v_exp_f32_e32 v73, v73
	v_sub_f32_e32 v72, v72, v26
	v_add_f32_e32 v28, v28, v76
	v_exp_f32_e32 v72, v72
	v_sub_f32_e32 v71, v71, v26
	v_add_f32_e32 v28, v28, v75
	v_exp_f32_e32 v71, v71
	v_sub_f32_e32 v70, v70, v26
	v_add_f32_e32 v28, v28, v74
	v_exp_f32_e32 v70, v70
	v_sub_f32_e32 v69, v69, v26
	v_add_f32_e32 v28, v28, v73
	v_exp_f32_e32 v69, v69
	v_sub_f32_e32 v68, v68, v26
	v_add_f32_e32 v28, v28, v72
	v_exp_f32_e32 v68, v68
	v_sub_f32_e32 v67, v67, v26
	v_add_f32_e32 v28, v28, v71
	v_exp_f32_e32 v67, v67
	v_sub_f32_e32 v66, v66, v26
	v_add_f32_e32 v28, v28, v70
	v_exp_f32_e32 v66, v66
	v_sub_f32_e32 v59, v59, v26
	v_add_f32_e32 v28, v28, v69
	v_exp_f32_e32 v59, v59
	v_sub_f32_e32 v58, v58, v26
	v_add_f32_e32 v28, v28, v68
	v_exp_f32_e32 v58, v58
	v_sub_f32_e32 v57, v57, v26
	v_add_f32_e32 v28, v28, v67
	v_exp_f32_e32 v57, v57
	v_sub_f32_e32 v56, v56, v26
	v_add_f32_e32 v28, v28, v66
	v_exp_f32_e32 v56, v56
	v_sub_f32_e32 v55, v55, v26
	v_add_f32_e32 v28, v28, v59
	v_exp_f32_e32 v55, v55
	v_sub_f32_e32 v54, v54, v26
	v_add_f32_e32 v28, v28, v58
	v_exp_f32_e32 v54, v54
	v_sub_f32_e32 v53, v53, v26
	v_add_f32_e32 v28, v28, v57
	v_exp_f32_e32 v53, v53
	v_sub_f32_e32 v52, v52, v26
	v_add_f32_e32 v28, v28, v56
	v_exp_f32_e32 v52, v52
	v_sub_f32_e32 v51, v51, v26
	v_add_f32_e32 v28, v28, v55
	v_exp_f32_e32 v51, v51
	v_sub_f32_e32 v50, v50, v26
	v_add_f32_e32 v28, v28, v54
	v_exp_f32_e32 v50, v50
	v_sub_f32_e32 v37, v37, v26
	v_add_f32_e32 v28, v28, v53
	v_exp_f32_e32 v93, v37
	v_sub_f32_e32 v36, v36, v26
	v_add_f32_e32 v28, v28, v52
	v_exp_f32_e32 v94, v36
	v_sub_f32_e32 v35, v35, v26
	v_add_f32_e32 v28, v28, v51
	v_exp_f32_e32 v95, v35
	v_sub_f32_e32 v34, v34, v26
	v_add_f32_e32 v28, v28, v50
	v_exp_f32_e32 v96, v34
	v_sub_f32_e32 v17, v17, v26
	v_add_f32_e32 v28, v28, v93
	v_exp_f32_e32 v97, v17
	v_sub_f32_e32 v16, v16, v26
	v_add_f32_e32 v28, v28, v94
	v_exp_f32_e32 v132, v16
	v_sub_f32_e32 v15, v15, v26
	v_add_f32_e32 v28, v28, v95
	v_exp_f32_e32 v133, v15
	v_sub_f32_e32 v14, v14, v26
	v_add_f32_e32 v28, v28, v96
	v_exp_f32_e32 v134, v14
	v_sub_f32_e32 v13, v13, v26
	v_add_f32_e32 v17, v28, v97
	v_exp_f32_e32 v135, v13
	v_sub_f32_e32 v12, v12, v26
	v_add_f32_e32 v16, v17, v132
	v_exp_f32_e32 v136, v12
	v_sub_f32_e32 v11, v11, v26
	v_add_f32_e32 v15, v16, v133
	v_exp_f32_e32 v137, v11
	v_add_f32_e32 v14, v15, v134
	v_add_f32_e32 v13, v14, v135
	v_add_f32_e32 v12, v13, v136
	v_add_f32_e32 v11, v12, v137
	v_sub_f32_e32 v12, v46, v26
	v_exp_f32_e32 v46, v12
	v_sub_f32_e32 v12, v44, v26
	v_exp_f32_e32 v138, v12
	v_sub_f32_e32 v12, v45, v26
	v_exp_f32_e32 v139, v12
	v_sub_f32_e32 v12, v42, v26
	v_exp_f32_e32 v140, v12
	v_sub_f32_e32 v12, v43, v26
	v_add_f32_e32 v11, v11, v46
	v_exp_f32_e32 v141, v12
	v_sub_f32_e32 v12, v40, v26
	v_add_f32_e32 v11, v11, v138
	v_exp_f32_e32 v142, v12
	v_sub_f32_e32 v12, v41, v26
	v_add_f32_e32 v11, v11, v139
	v_exp_f32_e32 v143, v12
	v_sub_f32_e32 v12, v38, v26
	v_add_f32_e32 v11, v11, v140
	v_exp_f32_e32 v144, v12
	v_sub_f32_e32 v12, v39, v26
	v_add_f32_e32 v11, v11, v141
	v_exp_f32_e32 v145, v12
	v_sub_f32_e32 v12, v24, v26
	v_add_f32_e32 v11, v11, v142
	v_exp_f32_e32 v146, v12
	v_sub_f32_e32 v12, v25, v26
	v_add_f32_e32 v11, v11, v143
	v_exp_f32_e32 v147, v12
	v_sub_f32_e32 v12, v22, v26
	v_add_f32_e32 v11, v11, v144
	v_exp_f32_e32 v148, v12
	v_sub_f32_e32 v12, v23, v26
	v_add_f32_e32 v11, v11, v145
	v_exp_f32_e32 v149, v12
	v_sub_f32_e32 v12, v20, v26
	v_add_f32_e32 v11, v11, v146
	v_exp_f32_e32 v150, v12
	v_sub_f32_e32 v12, v21, v26
	v_add_f32_e32 v11, v11, v147
	v_exp_f32_e32 v151, v12
	v_sub_f32_e32 v12, v18, v26
	v_add_f32_e32 v11, v11, v148
	v_exp_f32_e32 v152, v12
	v_sub_f32_e32 v12, v19, v26
	v_add_f32_e32 v11, v11, v149
	v_exp_f32_e32 v153, v12
	v_fma_f32 v2, v2, s9, -v26
	v_add_f32_e32 v11, v11, v150
	v_exp_f32_e32 v154, v2
	v_fma_f32 v3, v3, s9, -v26
	v_add_f32_e32 v11, v11, v151
	v_exp_f32_e32 v155, v3
	v_fma_f32 v3, v4, s9, -v26
	v_add_f32_e32 v11, v11, v152
	v_exp_f32_e32 v156, v3
	v_fma_f32 v3, v5, s9, -v26
	v_add_f32_e32 v11, v11, v153
	v_exp_f32_e32 v157, v3
	v_fma_f32 v3, v6, s9, -v26
	v_add_f32_e32 v2, v11, v154
	v_exp_f32_e32 v158, v3
	v_fma_f32 v3, v7, s9, -v26
	v_add_f32_e32 v2, v2, v155
	v_exp_f32_e32 v159, v3
	v_fma_f32 v3, v8, s9, -v26
	v_add_f32_e32 v2, v2, v156
	v_exp_f32_e32 v160, v3
	v_fma_f32 v3, v9, s9, -v26
	v_add_f32_e32 v2, v2, v157
	v_exp_f32_e32 v161, v3
	v_sub_f32_e32 v3, 0xf149f2ca, v26
	v_add_f32_e32 v2, v2, v158
	v_exp_f32_e32 v162, v3
	v_add_f32_e32 v2, v2, v159
	v_add_f32_e32 v2, v2, v160
	v_add_f32_e32 v2, v2, v161
	v_add_f32_e32 v2, v2, v162
	v_add_f32_e32 v2, v2, v162
	v_add_f32_e32 v2, v2, v162
	v_add_f32_e32 v2, v2, v162
	v_add_f32_e32 v2, v2, v162
	v_add_f32_e32 v2, v2, v162
	v_add_f32_e32 v2, v2, v162
	v_add_f32_e32 v163, v2, v162
	v_sub_f32_e32 v2, v201, v26
	v_add_u32_e32 v44, s7, v223
	v_exp_f32_e32 v165, v2
	s_nop 0
	v_cvt_pk_bf16_f32 v2, v10, v29
	s_nop 0
	v_cvt_pk_bf16_f32 v3, v30, v31
	s_nop 0
	v_cvt_pk_bf16_f32 v4, v32, v33
	s_nop 0
	v_cvt_pk_bf16_f32 v5, v47, v48
	ds_read_b64_tr_b16 v[6:7], v44 offset:32256
	ds_read_b64_tr_b16 v[8:9], v44 offset:33408
	ds_read_b64_tr_b16 v[10:11], v44 offset:32320
	ds_read_b64_tr_b16 v[12:13], v44 offset:33472
	ds_bpermute_b32 v164, v27, v163
	s_waitcnt lgkmcnt(3)
	v_mfma_f32_32x32x16_bf16 v[18:33], v[6:9], v[2:5], 0
	s_nop 0
	v_cvt_pk_bf16_f32 v34, v49, v60
	s_nop 0
	v_cvt_pk_bf16_f32 v35, v61, v62
	s_nop 0
	v_cvt_pk_bf16_f32 v36, v63, v64
	s_nop 0
	v_cvt_pk_bf16_f32 v37, v65, v79
	ds_read_b64_tr_b16 v[38:39], v44 offset:34560
	ds_read_b64_tr_b16 v[40:41], v44 offset:35712
	ds_read_b64_tr_b16 v[42:43], v44 offset:34624
	ds_read_b64_tr_b16 v[44:45], v44 offset:35776
	v_add_u32_e32 v47, s6, v223
	s_waitcnt lgkmcnt(5)
	v_mfma_f32_32x32x16_bf16 v[2:17], v[10:13], v[2:5], 0
	s_waitcnt lgkmcnt(2)
	v_mfma_f32_32x32x16_bf16 v[18:33], v[38:41], v[34:37], v[18:33]
	s_waitcnt lgkmcnt(0)
	v_mfma_f32_32x32x16_bf16 v[2:17], v[42:45], v[34:37], v[2:17]
	s_nop 0
	v_cvt_pk_bf16_f32 v34, v80, v81
	s_nop 0
	v_cvt_pk_bf16_f32 v35, v92, v91
	s_nop 0
	v_cvt_pk_bf16_f32 v36, v90, v89
	s_nop 0
	v_cvt_pk_bf16_f32 v37, v88, v87
	ds_read_b64_tr_b16 v[38:39], v47 offset:32256
	ds_read_b64_tr_b16 v[40:41], v47 offset:33408
	ds_read_b64_tr_b16 v[42:43], v47 offset:32320
	ds_read_b64_tr_b16 v[44:45], v47 offset:33472
	s_waitcnt lgkmcnt(2)
	v_mfma_f32_32x32x16_bf16 v[18:33], v[38:41], v[34:37], v[18:33]
	s_waitcnt lgkmcnt(0)
	v_mfma_f32_32x32x16_bf16 v[2:17], v[42:45], v[34:37], v[2:17]
	s_nop 0
	v_cvt_pk_bf16_f32 v34, v86, v85
	s_nop 0
	v_cvt_pk_bf16_f32 v35, v84, v83
	s_nop 0
	v_cvt_pk_bf16_f32 v36, v82, v78
	s_nop 0
	v_cvt_pk_bf16_f32 v37, v77, v76
	ds_read_b64_tr_b16 v[38:39], v47 offset:34560
	ds_read_b64_tr_b16 v[40:41], v47 offset:35712
	ds_read_b64_tr_b16 v[42:43], v47 offset:34624
	ds_read_b64_tr_b16 v[44:45], v47 offset:35776
	v_add_u32_e32 v47, s15, v223
	s_waitcnt lgkmcnt(2)
	v_mfma_f32_32x32x16_bf16 v[18:33], v[38:41], v[34:37], v[18:33]
	s_waitcnt lgkmcnt(0)
	v_mfma_f32_32x32x16_bf16 v[2:17], v[42:45], v[34:37], v[2:17]
	s_nop 0
	v_cvt_pk_bf16_f32 v34, v75, v74
	s_nop 0
	v_cvt_pk_bf16_f32 v35, v73, v72
	s_nop 0
	v_cvt_pk_bf16_f32 v36, v71, v70
	s_nop 0
	v_cvt_pk_bf16_f32 v37, v69, v68
	ds_read_b64_tr_b16 v[38:39], v47 offset:32256
	ds_read_b64_tr_b16 v[40:41], v47 offset:33408
	ds_read_b64_tr_b16 v[42:43], v47 offset:32320
	ds_read_b64_tr_b16 v[44:45], v47 offset:33472
	s_waitcnt lgkmcnt(2)
	v_mfma_f32_32x32x16_bf16 v[18:33], v[38:41], v[34:37], v[18:33]
	s_waitcnt lgkmcnt(0)
	v_mfma_f32_32x32x16_bf16 v[2:17], v[42:45], v[34:37], v[2:17]
	s_nop 0
	v_cvt_pk_bf16_f32 v34, v67, v66
	s_nop 0
	v_cvt_pk_bf16_f32 v35, v59, v58
	s_nop 0
	v_cvt_pk_bf16_f32 v36, v57, v56
	s_nop 0
	v_cvt_pk_bf16_f32 v37, v55, v54
	ds_read_b64_tr_b16 v[38:39], v47 offset:34560
	ds_read_b64_tr_b16 v[40:41], v47 offset:35712
	ds_read_b64_tr_b16 v[42:43], v47 offset:34624
	ds_read_b64_tr_b16 v[44:45], v47 offset:35776
	v_add_u32_e32 v47, s14, v223
	s_waitcnt lgkmcnt(2)
	v_mfma_f32_32x32x16_bf16 v[18:33], v[38:41], v[34:37], v[18:33]
	s_waitcnt lgkmcnt(0)
	v_mfma_f32_32x32x16_bf16 v[2:17], v[42:45], v[34:37], v[2:17]
	s_nop 0
	v_cvt_pk_bf16_f32 v34, v53, v52
	s_nop 0
	v_cvt_pk_bf16_f32 v35, v51, v50
	s_nop 0
	v_cvt_pk_bf16_f32 v36, v93, v94
	s_nop 0
	v_cvt_pk_bf16_f32 v37, v95, v96
	ds_read_b64_tr_b16 v[38:39], v47 offset:32256
	ds_read_b64_tr_b16 v[40:41], v47 offset:33408
	ds_read_b64_tr_b16 v[42:43], v47 offset:32320
	ds_read_b64_tr_b16 v[44:45], v47 offset:33472
	s_waitcnt lgkmcnt(2)
	v_mfma_f32_32x32x16_bf16 v[18:33], v[38:41], v[34:37], v[18:33]
	s_waitcnt lgkmcnt(0)
	v_mfma_f32_32x32x16_bf16 v[2:17], v[42:45], v[34:37], v[2:17]
	s_nop 0
	v_cvt_pk_bf16_f32 v34, v97, v132
	s_nop 0
	v_cvt_pk_bf16_f32 v35, v133, v134
	s_nop 0
	v_cvt_pk_bf16_f32 v36, v135, v136
	s_nop 0
	v_cvt_pk_bf16_f32 v37, v137, v46
	ds_read_b64_tr_b16 v[38:39], v47 offset:34560
	ds_read_b64_tr_b16 v[40:41], v47 offset:35712
	ds_read_b64_tr_b16 v[42:43], v47 offset:34624
	ds_read_b64_tr_b16 v[44:45], v47 offset:35776
	v_add_u32_e32 v46, s0, v223
	s_waitcnt lgkmcnt(2)
	v_mfma_f32_32x32x16_bf16 v[18:33], v[38:41], v[34:37], v[18:33]
	s_waitcnt lgkmcnt(0)
	v_mfma_f32_32x32x16_bf16 v[2:17], v[42:45], v[34:37], v[2:17]
	s_nop 0
	v_cvt_pk_bf16_f32 v34, v138, v139
	s_nop 0
	v_cvt_pk_bf16_f32 v35, v140, v141
	s_nop 0
	v_cvt_pk_bf16_f32 v36, v142, v143
	s_nop 0
	v_cvt_pk_bf16_f32 v37, v144, v145
	ds_read_b64_tr_b16 v[38:39], v46 offset:32256
	ds_read_b64_tr_b16 v[40:41], v46 offset:33408
	ds_read_b64_tr_b16 v[42:43], v46 offset:32320
	ds_read_b64_tr_b16 v[44:45], v46 offset:33472
	s_waitcnt lgkmcnt(2)
	v_mfma_f32_32x32x16_bf16 v[18:33], v[38:41], v[34:37], v[18:33]
	s_waitcnt lgkmcnt(0)
	v_mfma_f32_32x32x16_bf16 v[2:17], v[42:45], v[34:37], v[2:17]
	s_nop 0
	v_cvt_pk_bf16_f32 v34, v146, v147
	s_nop 0
	v_cvt_pk_bf16_f32 v35, v148, v149
	s_nop 0
	v_cvt_pk_bf16_f32 v36, v150, v151
	s_nop 0
	v_cvt_pk_bf16_f32 v37, v152, v153
	ds_read_b64_tr_b16 v[38:39], v46 offset:34560
	ds_read_b64_tr_b16 v[40:41], v46 offset:35712
	ds_read_b64_tr_b16 v[42:43], v46 offset:34624
	ds_read_b64_tr_b16 v[44:45], v46 offset:35776
	s_waitcnt lgkmcnt(2)
	v_mfma_f32_32x32x16_bf16 v[18:33], v[38:41], v[34:37], v[18:33]
	s_waitcnt lgkmcnt(0)
	v_mfma_f32_32x32x16_bf16 v[2:17], v[42:45], v[34:37], v[2:17]
	s_nop 0
	v_cvt_pk_bf16_f32 v34, v154, v155
	s_nop 0
	v_cvt_pk_bf16_f32 v35, v156, v157
	s_nop 0
	v_cvt_pk_bf16_f32 v36, v158, v159
	s_nop 0
	v_cvt_pk_bf16_f32 v37, v160, v161
	ds_read_b64_tr_b16 v[38:39], v223 offset:59904
	ds_read_b64_tr_b16 v[40:41], v223 offset:61056
	ds_read_b64_tr_b16 v[42:43], v223 offset:59968
	ds_read_b64_tr_b16 v[44:45], v223 offset:61120
	s_waitcnt lgkmcnt(2)
	v_mfma_f32_32x32x16_bf16 v[18:33], v[38:41], v[34:37], v[18:33]
	s_waitcnt lgkmcnt(0)
	v_mfma_f32_32x32x16_bf16 v[2:17], v[42:45], v[34:37], v[2:17]
	s_nop 0
	v_cvt_pk_bf16_f32 v34, v162, v162
	s_nop 0
	v_cvt_pk_bf16_f32 v35, v162, v162
	s_nop 0
	v_cvt_pk_bf16_f32 v36, v162, v162
	s_nop 0
	v_cvt_pk_bf16_f32 v37, v162, v162
	ds_read_b64_tr_b16 v[38:39], v223 offset:62208
	ds_read_b64_tr_b16 v[40:41], v223 offset:63360
	ds_read_b64_tr_b16 v[42:43], v223 offset:62272
	ds_read_b64_tr_b16 v[44:45], v223 offset:63424
	s_waitcnt lgkmcnt(2)
	v_mfma_f32_32x32x16_bf16 v[18:33], v[38:41], v[34:37], v[18:33]
	s_waitcnt lgkmcnt(0)
	v_mfma_f32_32x32x16_bf16 v[2:17], v[42:45], v[34:37], v[2:17]
	v_add_f32_e32 v34, v163, v164
	v_add_f32_e32 v34, v165, v34
	v_div_scale_f32 v35, s[0:1], v34, v34, 1.0
	v_rcp_f32_e32 v36, v35
	s_nop 0
	v_fma_f32 v37, -v35, v36, 1.0
	v_fmac_f32_e32 v36, v37, v36
	v_div_scale_f32 v37, vcc, 1.0, v34, 1.0
	v_mul_f32_e32 v38, v37, v36
	v_fma_f32 v39, -v35, v38, v37
	v_fmac_f32_e32 v38, v39, v36
	v_fma_f32 v35, -v35, v38, v37
	v_div_fmas_f32 v35, v35, v36, v38
	v_div_fixup_f32 v36, v35, v34, 1.0
	v_mul_f32_e32 v36, 0x42c80000, v36
	v_mul_f32_e32 v3, v36, v3
	v_mul_f32_e32 v2, v36, v2
	v_mul_f32_e32 v4, v36, v4
	v_mul_f32_e32 v5, v36, v5
	v_med3_f32 v3, v3, s13, v227
	v_med3_f32 v2, v2, s13, v227
	v_rndne_f32_e32 v3, v3
	v_med3_f32 v4, v4, s13, v227
	v_med3_f32 v5, v5, s13, v227
	v_rndne_f32_e32 v2, v2
	v_cvt_i32_f32_e32 v3, v3
	v_rndne_f32_e32 v4, v4
	v_rndne_f32_e32 v5, v5
	v_cvt_i32_f32_e32 v2, v2
	v_cvt_i32_f32_sdwa v4, v4 dst_sel:WORD_1 dst_unused:UNUSED_PAD src0_sel:DWORD
	v_cvt_i32_f32_e32 v5, v5
	v_lshlrev_b32_e32 v3, 8, v3
	v_and_b32_e32 v3, 0xff00, v3
	v_and_b32_e32 v4, 0xff0000, v4
	v_perm_b32 v2, v5, v2, s33
	v_lshl_add_u64 v[34:35], v[214:215], 0, v[216:217]
	v_or3_b32 v2, v2, v3, v4
	v_mul_f32_e32 v3, v36, v23
	global_store_dword v[34:35], v2, off offset:32
	v_mul_f32_e32 v2, v36, v22
	v_mul_f32_e32 v4, v36, v24
	v_mul_f32_e32 v5, v36, v25
	v_med3_f32 v3, v3, s13, v227
	v_med3_f32 v2, v2, s13, v227
	v_rndne_f32_e32 v3, v3
	v_med3_f32 v4, v4, s13, v227
	v_med3_f32 v5, v5, s13, v227
	v_rndne_f32_e32 v2, v2
	v_cvt_i32_f32_e32 v3, v3
	v_rndne_f32_e32 v4, v4
	v_rndne_f32_e32 v5, v5
	v_cvt_i32_f32_e32 v2, v2
	v_cvt_i32_f32_sdwa v4, v4 dst_sel:WORD_1 dst_unused:UNUSED_PAD src0_sel:DWORD
	v_cvt_i32_f32_e32 v5, v5
	v_lshlrev_b32_e32 v3, 8, v3
	v_and_b32_e32 v3, 0xff00, v3
	v_and_b32_e32 v4, 0xff0000, v4
	v_perm_b32 v2, v5, v2, s33
	v_or3_b32 v2, v2, v3, v4
	v_mul_f32_e32 v3, v36, v7
	global_store_dword v[34:35], v2, off offset:8
	v_mul_f32_e32 v2, v36, v6
	v_mul_f32_e32 v4, v36, v8
	v_mul_f32_e32 v5, v36, v9
	v_med3_f32 v3, v3, s13, v227
	v_med3_f32 v2, v2, s13, v227
	v_rndne_f32_e32 v3, v3
	v_med3_f32 v4, v4, s13, v227
	v_med3_f32 v5, v5, s13, v227
	v_rndne_f32_e32 v2, v2
	v_cvt_i32_f32_e32 v3, v3
	v_rndne_f32_e32 v4, v4
	v_rndne_f32_e32 v5, v5
	v_cvt_i32_f32_e32 v2, v2
	v_cvt_i32_f32_sdwa v4, v4 dst_sel:WORD_1 dst_unused:UNUSED_PAD src0_sel:DWORD
	v_cvt_i32_f32_e32 v5, v5
	v_lshlrev_b32_e32 v3, 8, v3
	v_and_b32_e32 v3, 0xff00, v3
	v_and_b32_e32 v4, 0xff0000, v4
	v_perm_b32 v2, v5, v2, s33
	v_or3_b32 v2, v2, v3, v4
	v_mul_f32_e32 v3, v36, v27
	global_store_dword v[34:35], v2, off offset:40
	v_mul_f32_e32 v2, v36, v26
	v_mul_f32_e32 v4, v36, v28
	v_mul_f32_e32 v5, v36, v29
	v_med3_f32 v3, v3, s13, v227
	v_med3_f32 v2, v2, s13, v227
	v_rndne_f32_e32 v3, v3
	v_med3_f32 v4, v4, s13, v227
	v_med3_f32 v5, v5, s13, v227
	v_rndne_f32_e32 v2, v2
	v_cvt_i32_f32_e32 v3, v3
	v_rndne_f32_e32 v4, v4
	v_rndne_f32_e32 v5, v5
	v_cvt_i32_f32_e32 v2, v2
	v_cvt_i32_f32_sdwa v4, v4 dst_sel:WORD_1 dst_unused:UNUSED_PAD src0_sel:DWORD
	v_cvt_i32_f32_e32 v5, v5
	v_lshlrev_b32_e32 v3, 8, v3
	v_and_b32_e32 v3, 0xff00, v3
	v_and_b32_e32 v4, 0xff0000, v4
	v_perm_b32 v2, v5, v2, s33
	v_or3_b32 v2, v2, v3, v4
	v_mul_f32_e32 v3, v36, v11
	global_store_dword v[34:35], v2, off offset:16
	v_mul_f32_e32 v2, v36, v10
	v_mul_f32_e32 v4, v36, v12
	v_mul_f32_e32 v5, v36, v13
	v_med3_f32 v3, v3, s13, v227
	v_med3_f32 v2, v2, s13, v227
	v_rndne_f32_e32 v3, v3
	v_med3_f32 v4, v4, s13, v227
	v_med3_f32 v5, v5, s13, v227
	v_rndne_f32_e32 v2, v2
	v_cvt_i32_f32_e32 v3, v3
	v_rndne_f32_e32 v4, v4
	v_rndne_f32_e32 v5, v5
	v_cvt_i32_f32_e32 v2, v2
	v_cvt_i32_f32_sdwa v4, v4 dst_sel:WORD_1 dst_unused:UNUSED_PAD src0_sel:DWORD
	v_cvt_i32_f32_e32 v5, v5
	v_lshlrev_b32_e32 v3, 8, v3
	v_and_b32_e32 v3, 0xff00, v3
	v_and_b32_e32 v4, 0xff0000, v4
	v_perm_b32 v2, v5, v2, s33
	v_or3_b32 v2, v2, v3, v4
	v_mul_f32_e32 v3, v36, v31
	global_store_dword v[34:35], v2, off offset:48
	v_mul_f32_e32 v2, v36, v30
	v_mul_f32_e32 v4, v36, v32
	v_mul_f32_e32 v5, v36, v33
	v_med3_f32 v3, v3, s13, v227
	v_med3_f32 v2, v2, s13, v227
	v_rndne_f32_e32 v3, v3
	v_med3_f32 v4, v4, s13, v227
	v_med3_f32 v5, v5, s13, v227
	v_rndne_f32_e32 v2, v2
	v_cvt_i32_f32_e32 v3, v3
	v_rndne_f32_e32 v4, v4
	v_rndne_f32_e32 v5, v5
	v_cvt_i32_f32_e32 v2, v2
	v_cvt_i32_f32_sdwa v4, v4 dst_sel:WORD_1 dst_unused:UNUSED_PAD src0_sel:DWORD
	v_cvt_i32_f32_e32 v5, v5
	v_lshlrev_b32_e32 v3, 8, v3
	v_and_b32_e32 v3, 0xff00, v3
	v_and_b32_e32 v4, 0xff0000, v4
	v_perm_b32 v2, v5, v2, s33
	v_mul_f32_e32 v19, v36, v19
	v_or3_b32 v2, v2, v3, v4
	v_mul_f32_e32 v3, v36, v15
	v_mul_f32_e32 v18, v36, v18
	v_mul_f32_e32 v20, v36, v20
	v_mul_f32_e32 v21, v36, v21
	v_med3_f32 v19, v19, s13, v227
	global_store_dword v[34:35], v2, off offset:24
	v_mul_f32_e32 v2, v36, v14
	v_mul_f32_e32 v4, v36, v16
	v_mul_f32_e32 v5, v36, v17
	v_med3_f32 v3, v3, s13, v227
	v_med3_f32 v18, v18, s13, v227
	v_rndne_f32_e32 v19, v19
	v_med3_f32 v20, v20, s13, v227
	v_med3_f32 v21, v21, s13, v227
	v_med3_f32 v2, v2, s13, v227
	v_rndne_f32_e32 v3, v3
	v_med3_f32 v4, v4, s13, v227
	v_med3_f32 v5, v5, s13, v227
	v_rndne_f32_e32 v18, v18
	v_cvt_i32_f32_e32 v19, v19
	v_rndne_f32_e32 v20, v20
	v_rndne_f32_e32 v21, v21
	v_rndne_f32_e32 v2, v2
	v_cvt_i32_f32_e32 v3, v3
	v_rndne_f32_e32 v4, v4
	v_rndne_f32_e32 v5, v5
	v_cvt_i32_f32_e32 v18, v18
	v_cvt_i32_f32_sdwa v20, v20 dst_sel:WORD_1 dst_unused:UNUSED_PAD src0_sel:DWORD
	v_cvt_i32_f32_e32 v21, v21
	v_cvt_i32_f32_e32 v2, v2
	v_cvt_i32_f32_sdwa v4, v4 dst_sel:WORD_1 dst_unused:UNUSED_PAD src0_sel:DWORD
	v_cvt_i32_f32_e32 v5, v5
	v_lshlrev_b32_e32 v19, 8, v19
	v_lshlrev_b32_e32 v3, 8, v3
	v_and_b32_e32 v19, 0xff00, v19
	v_and_b32_e32 v20, 0xff0000, v20
	v_perm_b32 v18, v21, v18, s33
	v_and_b32_e32 v3, 0xff00, v3
	v_and_b32_e32 v4, 0xff0000, v4
	v_perm_b32 v2, v5, v2, s33
	v_or3_b32 v18, v18, v19, v20
	v_or3_b32 v2, v2, v3, v4
	s_and_b64 vcc, exec, s[16:17]
	s_mov_b32 s16, 1
	global_store_dword v[34:35], v18, off
	global_store_dword v[34:35], v2, off offset:56
	v_lshl_or_b32 v2, s16, 5, v127
	v_ashrrev_i32_e32 v3, 31, v2
	v_lshlrev_b64 v[216:217], 12, v[2:3]
	v_lshl_add_u64 v[6:7], v[212:213], 0, v[216:217]
	s_mul_i32 s7, s16, 0x1200
	s_add_i32 s6, s7, 0x1200
	s_add_i32 s15, s7, 0x2400
	v_add_u32_e32 v18, s7, v222
	v_add_u32_e32 v34, s6, v222
	v_add_u32_e32 v51, s15, v222
	s_add_i32 s14, s7, 0x3600
	ds_read_b128 v[6:9], v18
	ds_read_b128 v[10:13], v18 offset:32
	ds_read_b128 v[14:17], v18 offset:64
	ds_read_b128 v[18:21], v18 offset:96
	ds_read_b128 v[22:25], v34
	ds_read_b128 v[26:29], v34 offset:32
	ds_read_b128 v[30:33], v34 offset:64
	ds_read_b128 v[34:37], v34 offset:96
	s_or_b32 s1, s16, 2
	ds_read_b128 v[38:41], v51
	ds_read_b128 v[42:45], v51 offset:32
	ds_read_b128 v[46:49], v51 offset:64
	ds_read_b128 v[144:147], v51 offset:96
	v_add_u32_e32 v51, s14, v222
	s_or_b32 s20, s16, 4
	s_add_i32 s0, s7, 0x4800
	ds_read_b128 v[148:151], v51
	ds_read_b128 v[152:155], v51 offset:32
	ds_read_b128 v[156:159], v51 offset:64
	ds_read_b128 v[160:163], v51 offset:96
	v_add_u32_e32 v51, s0, v222
	s_cmp_le_i32 s96, s16
	v_cndmask_b32_e64 v50, 0, 1, s[18:19]
	ds_read_b128 v[180:183], v51
	ds_read_b128 v[184:187], v51 offset:32
	ds_read_b128 v[188:191], v51 offset:64
	ds_read_b128 v[192:195], v51 offset:96
	ds_read_b128 v[164:167], v222 offset:27648
	ds_read_b128 v[168:171], v222 offset:27680
	ds_read_b128 v[172:175], v222 offset:27712
	ds_read_b128 v[176:179], v222 offset:27744
	v_mov_b32_e32 v51, v224
	s_cselect_b64 s[18:19], -1, 0
	s_or_b64 s[18:19], s[2:3], s[18:19]
	v_cmp_gt_i32_e32 vcc, 0, v51
	s_and_b64 s[86:87], vcc, s[18:19]
	v_cmp_gt_i32_e32 vcc, 1, v51
	s_and_b64 s[82:83], vcc, s[18:19]
	v_cmp_gt_i32_e32 vcc, 2, v51
	s_and_b64 s[84:85], vcc, s[18:19]
	v_cmp_gt_i32_e32 vcc, 3, v51
	s_and_b64 s[78:79], vcc, s[18:19]
	v_cmp_gt_i32_e32 vcc, 8, v51
	s_and_b64 s[80:81], vcc, s[18:19]
	v_cmp_gt_i32_e32 vcc, 9, v51
	s_and_b64 s[74:75], vcc, s[18:19]
	v_cmp_gt_i32_e32 vcc, 10, v51
	s_and_b64 s[76:77], vcc, s[18:19]
	v_cmp_gt_i32_e32 vcc, 11, v51
	s_and_b64 s[70:71], vcc, s[18:19]
	v_cmp_gt_i32_e32 vcc, 16, v51
	s_and_b64 s[72:73], vcc, s[18:19]
	v_cmp_gt_i32_e32 vcc, 17, v51
	s_and_b64 s[66:67], vcc, s[18:19]
	v_cmp_gt_i32_e32 vcc, 18, v51
	s_and_b64 s[68:69], vcc, s[18:19]
	v_cmp_gt_i32_e32 vcc, 19, v51
	s_and_b64 s[62:63], vcc, s[18:19]
	v_cmp_gt_i32_e32 vcc, 24, v51
	s_and_b64 s[64:65], vcc, s[18:19]
	v_cmp_gt_i32_e32 vcc, 25, v51
	s_and_b64 s[58:59], vcc, s[18:19]
	v_cmp_gt_i32_e32 vcc, 26, v51
	s_and_b64 s[60:61], vcc, s[18:19]
	v_cmp_gt_i32_e32 vcc, 27, v51
	s_and_b64 s[56:57], vcc, s[18:19]
	s_cmp_ge_i32 s16, s4
	s_cselect_b64 s[18:19], -1, 0
	s_or_b64 s[54:55], s[2:3], s[18:19]
	s_cmp_le_i32 s96, s1
	s_cselect_b64 s[18:19], -1, 0
	s_or_b64 s[52:53], s[2:3], s[18:19]
	s_cmp_ge_i32 s16, s97
	s_cselect_b64 s[16:17], -1, 0
	s_or_b64 s[36:37], s[2:3], s[16:17]
	s_cmp_le_i32 s96, s20
	s_cselect_b64 s[16:17], -1, 0
	s_or_b64 s[16:17], s[2:3], s[16:17]
	v_cmp_lt_i32_e32 vcc, -1, v51
	s_and_b64 s[50:51], vcc, s[16:17]
	v_cmp_lt_i32_e32 vcc, 0, v51
	s_and_b64 s[46:47], vcc, s[16:17]
	v_cmp_lt_i32_e32 vcc, 1, v51
	s_and_b64 s[48:49], vcc, s[16:17]
	v_cmp_lt_i32_e32 vcc, 2, v51
	s_and_b64 s[42:43], vcc, s[16:17]
	v_cmp_lt_i32_e32 vcc, 7, v51
	s_and_b64 s[44:45], vcc, s[16:17]
	v_cmp_lt_i32_e32 vcc, 8, v51
	s_and_b64 s[38:39], vcc, s[16:17]
	v_cmp_lt_i32_e32 vcc, 9, v51
	s_and_b64 s[40:41], vcc, s[16:17]
	v_cmp_lt_i32_e32 vcc, 10, v51
	s_and_b64 s[30:31], vcc, s[16:17]
	v_cmp_lt_i32_e32 vcc, 15, v51
	s_waitcnt vmcnt(8) lgkmcnt(14)
	v_mfma_f32_32x32x16_bf16 v[82:97], v[6:9], v[236:239], 0
	s_and_b64 s[34:35], vcc, s[16:17]
	v_cmp_lt_i32_e32 vcc, 16, v51
	s_and_b64 s[26:27], vcc, s[16:17]
	v_cmp_lt_i32_e32 vcc, 17, v51
	s_and_b64 s[28:29], vcc, s[16:17]
	v_cmp_lt_i32_e32 vcc, 18, v51
	s_and_b64 s[22:23], vcc, s[16:17]
	v_mfma_f32_32x32x16_bf16 v[66:81], v[22:25], v[236:239], 0
	v_cmp_lt_i32_e32 vcc, 23, v51
	s_and_b64 s[24:25], vcc, s[16:17]
	v_cmp_lt_i32_e32 vcc, 24, v51
	s_and_b64 s[18:19], vcc, s[16:17]
	v_cmp_lt_i32_e32 vcc, 25, v51
	s_and_b64 s[20:21], vcc, s[16:17]
	v_cmp_lt_i32_e32 vcc, 26, v51
	s_and_b64 vcc, vcc, s[16:17]
	v_cmp_ne_u32_e64 s[16:17], 1, v50
	v_mfma_f32_32x32x16_bf16 v[82:97], v[10:13], v[240:243], v[82:97]
	s_mov_b32 s1, 0xf149f2ca
	v_mfma_f32_32x32x16_bf16 v[66:81], v[26:29], v[240:243], v[66:81]
	v_mfma_f32_32x32x16_bf16 v[50:65], v[38:41], v[236:239], 0
	v_mfma_f32_32x32x16_bf16 v[82:97], v[14:17], v[244:247], v[82:97]
	v_mfma_f32_32x32x16_bf16 v[66:81], v[30:33], v[244:247], v[66:81]
	v_mfma_f32_32x32x16_bf16 v[50:65], v[42:45], v[240:243], v[50:65]
	v_mfma_f32_32x32x16_bf16 v[82:97], v[18:21], v[248:251], v[82:97]
	v_mfma_f32_32x32x16_bf16 v[66:81], v[34:37], v[248:251], v[66:81]
	s_waitcnt lgkmcnt(13)
	v_mfma_f32_32x32x16_bf16 v[50:65], v[46:49], v[244:247], v[50:65]
	s_waitcnt lgkmcnt(11)
	v_mfma_f32_32x32x16_bf16 v[34:49], v[148:151], v[236:239], 0
	s_waitcnt lgkmcnt(7)
	v_mfma_f32_32x32x16_bf16 v[18:33], v[180:183], v[236:239], 0
	s_waitcnt lgkmcnt(3)
	v_mfma_f32_32x32x16_bf16 v[2:17], v[164:167], v[236:239], 0
	s_waitcnt lgkmcnt(2)
	v_mfma_f32_32x32x16_bf16 v[2:17], v[168:171], v[240:243], v[2:17]
	v_mfma_f32_32x32x16_bf16 v[34:49], v[152:155], v[240:243], v[34:49]
	v_mfma_f32_32x32x16_bf16 v[18:33], v[184:187], v[240:243], v[18:33]
	s_waitcnt lgkmcnt(1)
	v_mfma_f32_32x32x16_bf16 v[2:17], v[172:175], v[244:247], v[2:17]
	v_mfma_f32_32x32x16_bf16 v[34:49], v[156:159], v[244:247], v[34:49]
	v_mfma_f32_32x32x16_bf16 v[18:33], v[188:191], v[244:247], v[18:33]
	s_waitcnt lgkmcnt(0)
	v_mfma_f32_32x32x16_bf16 v[2:17], v[176:179], v[248:251], v[2:17]
	v_mfma_f32_32x32x16_bf16 v[50:65], v[144:147], v[248:251], v[50:65]
	s_nop 10
	v_mul_f32_e32 v12, 0x3fb8aa3b, v83
	v_cndmask_b32_e64 v144, v226, v12, s[82:83]
	v_mul_f32_e32 v12, 0x3fb8aa3b, v84
	v_mul_f32_e32 v10, 0x3fb8aa3b, v82
	v_cndmask_b32_e64 v10, v226, v10, s[86:87]
	v_max_f32_e32 v11, v201, v201
	v_max_f32_e32 v11, v11, v10
	v_mfma_f32_32x32x16_bf16 v[34:49], v[160:163], v[248:251], v[34:49]
	v_mfma_f32_32x32x16_bf16 v[18:33], v[192:195], v[248:251], v[18:33]
	v_cndmask_b32_e64 v142, v226, v12, s[84:85]
	v_mul_f32_e32 v12, 0x3fb8aa3b, v85
	v_cndmask_b32_e64 v143, v226, v12, s[78:79]
	v_mul_f32_e32 v12, 0x3fb8aa3b, v86
	v_cndmask_b32_e64 v140, v226, v12, s[80:81]
	v_mul_f32_e32 v12, 0x3fb8aa3b, v87
	v_cndmask_b32_e64 v141, v226, v12, s[74:75]
	v_mul_f32_e32 v12, 0x3fb8aa3b, v88
	v_cndmask_b32_e64 v138, v226, v12, s[76:77]
	v_mul_f32_e32 v12, 0x3fb8aa3b, v89
	v_cndmask_b32_e64 v139, v226, v12, s[70:71]
	v_mul_f32_e32 v12, 0x3fb8aa3b, v90
	v_cndmask_b32_e64 v136, v226, v12, s[72:73]
	v_mul_f32_e32 v12, 0x3fb8aa3b, v91
	v_max3_f32 v11, v11, v144, v142
	v_cndmask_b32_e64 v137, v226, v12, s[66:67]
	v_mul_f32_e32 v12, 0x3fb8aa3b, v92
	v_max3_f32 v11, v11, v143, v140
	v_cndmask_b32_e64 v134, v226, v12, s[68:69]
	v_mul_f32_e32 v12, 0x3fb8aa3b, v93
	v_max3_f32 v11, v11, v141, v138
	v_cndmask_b32_e64 v135, v226, v12, s[62:63]
	v_mul_f32_e32 v12, 0x3fb8aa3b, v94
	v_max3_f32 v11, v11, v139, v136
	v_cndmask_b32_e64 v132, v226, v12, s[64:65]
	v_mul_f32_e32 v12, 0x3fb8aa3b, v95
	v_max3_f32 v11, v11, v137, v134
	v_cndmask_b32_e64 v133, v226, v12, s[58:59]
	v_mul_f32_e32 v12, 0x3fb8aa3b, v96
	v_max3_f32 v11, v11, v135, v132
	v_cndmask_b32_e64 v95, v226, v12, s[60:61]
	v_max3_f32 v145, v11, v133, v95
	v_mul_f32_e32 v11, 0x3fb8aa3b, v97
	v_cndmask_b32_e64 v96, v226, v11, s[56:57]
	v_mul_f32_e32 v11, 0x3fb8aa3b, v66
	v_cndmask_b32_e64 v94, v226, v11, s[54:55]
	v_mul_f32_e32 v11, 0x3fb8aa3b, v67
	v_cndmask_b32_e64 v93, v226, v11, s[54:55]
	v_mul_f32_e32 v11, 0x3fb8aa3b, v68
	v_cndmask_b32_e64 v92, v226, v11, s[54:55]
	v_mul_f32_e32 v11, 0x3fb8aa3b, v69
	v_cndmask_b32_e64 v91, v226, v11, s[54:55]
	v_mul_f32_e32 v11, 0x3fb8aa3b, v70
	v_cndmask_b32_e64 v90, v226, v11, s[54:55]
	v_mul_f32_e32 v11, 0x3fb8aa3b, v71
	v_cndmask_b32_e64 v89, v226, v11, s[54:55]
	v_mul_f32_e32 v11, 0x3fb8aa3b, v72
	v_cndmask_b32_e64 v88, v226, v11, s[54:55]
	v_mul_f32_e32 v11, 0x3fb8aa3b, v73
	v_cndmask_b32_e64 v87, v226, v11, s[54:55]
	v_mul_f32_e32 v11, 0x3fb8aa3b, v74
	v_cndmask_b32_e64 v86, v226, v11, s[54:55]
	v_mul_f32_e32 v11, 0x3fb8aa3b, v75
	v_cndmask_b32_e64 v85, v226, v11, s[54:55]
	v_mul_f32_e32 v11, 0x3fb8aa3b, v76
	v_cndmask_b32_e64 v84, v226, v11, s[54:55]
	v_mul_f32_e32 v11, 0x3fb8aa3b, v77
	v_cndmask_b32_e64 v83, v226, v11, s[54:55]
	v_mul_f32_e32 v11, 0x3fb8aa3b, v78
	v_cndmask_b32_e64 v82, v226, v11, s[54:55]
	v_mul_f32_e32 v11, 0x3fb8aa3b, v79
	v_cndmask_b32_e64 v78, v226, v11, s[54:55]
	v_mul_f32_e32 v11, 0x3fb8aa3b, v80
	v_cndmask_b32_e64 v77, v226, v11, s[54:55]
	v_mul_f32_e32 v11, 0x3fb8aa3b, v81
	v_cndmask_b32_e64 v76, v226, v11, s[54:55]
	v_mul_f32_e32 v11, 0x3fb8aa3b, v50
	v_cndmask_b32_e64 v75, v226, v11, s[52:53]
	v_mul_f32_e32 v11, 0x3fb8aa3b, v51
	v_cndmask_b32_e64 v74, v226, v11, s[52:53]
	v_mul_f32_e32 v11, 0x3fb8aa3b, v52
	v_cndmask_b32_e64 v73, v226, v11, s[52:53]
	v_mul_f32_e32 v11, 0x3fb8aa3b, v53
	v_cndmask_b32_e64 v72, v226, v11, s[52:53]
	v_mul_f32_e32 v11, 0x3fb8aa3b, v54
	v_cndmask_b32_e64 v71, v226, v11, s[52:53]
	v_mul_f32_e32 v11, 0x3fb8aa3b, v55
	v_cndmask_b32_e64 v70, v226, v11, s[52:53]
	v_mul_f32_e32 v11, 0x3fb8aa3b, v56
	v_cndmask_b32_e64 v69, v226, v11, s[52:53]
	v_mul_f32_e32 v11, 0x3fb8aa3b, v57
	v_cndmask_b32_e64 v68, v226, v11, s[52:53]
	v_mul_f32_e32 v11, 0x3fb8aa3b, v58
	v_cndmask_b32_e64 v67, v226, v11, s[52:53]
	v_mul_f32_e32 v11, 0x3fb8aa3b, v59
	v_cndmask_b32_e64 v66, v226, v11, s[52:53]
	v_mul_f32_e32 v11, 0x3fb8aa3b, v60
	v_cndmask_b32_e64 v59, v226, v11, s[52:53]
	v_mul_f32_e32 v11, 0x3fb8aa3b, v61
	v_cndmask_b32_e64 v58, v226, v11, s[52:53]
	v_mul_f32_e32 v11, 0x3fb8aa3b, v62
	v_cndmask_b32_e64 v57, v226, v11, s[52:53]
	v_mul_f32_e32 v11, 0x3fb8aa3b, v63
	v_cndmask_b32_e64 v56, v226, v11, s[52:53]
	v_mul_f32_e32 v11, 0x3fb8aa3b, v64
	v_cndmask_b32_e64 v55, v226, v11, s[52:53]
	v_mul_f32_e32 v11, 0x3fb8aa3b, v65
	v_cndmask_b32_e64 v54, v226, v11, s[52:53]
	v_mul_f32_e32 v11, 0x3fb8aa3b, v34
	v_cndmask_b32_e64 v53, v226, v11, s[36:37]
	v_mul_f32_e32 v11, 0x3fb8aa3b, v35
	v_cndmask_b32_e64 v52, v226, v11, s[36:37]
	v_mul_f32_e32 v11, 0x3fb8aa3b, v36
	v_cndmask_b32_e64 v51, v226, v11, s[36:37]
	v_mul_f32_e32 v11, 0x3fb8aa3b, v37
	v_cndmask_b32_e64 v50, v226, v11, s[36:37]
	v_mul_f32_e32 v11, 0x3fb8aa3b, v38
	v_max3_f32 v38, v145, v96, v94
	v_max3_f32 v38, v38, v93, v92
	v_max3_f32 v38, v38, v91, v90
	v_max3_f32 v38, v38, v89, v88
	v_max3_f32 v38, v38, v87, v86
	v_max3_f32 v38, v38, v85, v84
	v_max3_f32 v38, v38, v83, v82
	v_max3_f32 v38, v38, v78, v77
	v_max3_f32 v38, v38, v76, v75
	v_max3_f32 v38, v38, v74, v73
	v_max3_f32 v38, v38, v72, v71
	v_max3_f32 v38, v38, v70, v69
	v_cndmask_b32_e64 v37, v226, v11, s[36:37]
	v_mul_f32_e32 v11, 0x3fb8aa3b, v39
	v_max3_f32 v38, v38, v68, v67
	v_cndmask_b32_e64 v36, v226, v11, s[36:37]
	v_mul_f32_e32 v11, 0x3fb8aa3b, v40
	v_max3_f32 v38, v38, v66, v59
	v_cndmask_b32_e64 v35, v226, v11, s[36:37]
	v_mul_f32_e32 v11, 0x3fb8aa3b, v41
	v_max3_f32 v38, v38, v58, v57
	v_cndmask_b32_e64 v34, v226, v11, s[36:37]
	v_mul_f32_e32 v11, 0x3fb8aa3b, v42
	v_max3_f32 v38, v38, v56, v55
	v_cndmask_b32_e64 v17, v226, v11, s[36:37]
	v_mul_f32_e32 v11, 0x3fb8aa3b, v43
	v_max3_f32 v38, v38, v54, v53
	v_cndmask_b32_e64 v16, v226, v11, s[36:37]
	v_mul_f32_e32 v11, 0x3fb8aa3b, v44
	v_max3_f32 v38, v38, v52, v51
	v_cndmask_b32_e64 v15, v226, v11, s[36:37]
	v_mul_f32_e32 v11, 0x3fb8aa3b, v45
	v_max3_f32 v38, v38, v50, v37
	v_mul_f32_e32 v19, 0x3fb8aa3b, v19
	v_cndmask_b32_e64 v14, v226, v11, s[36:37]
	v_mul_f32_e32 v11, 0x3fb8aa3b, v46
	v_max3_f32 v38, v38, v36, v35
	v_cndmask_b32_e64 v45, v226, v19, s[46:47]
	v_mul_f32_e32 v19, 0x3fb8aa3b, v20
	v_cndmask_b32_e64 v13, v226, v11, s[36:37]
	v_mul_f32_e32 v11, 0x3fb8aa3b, v47
	v_max3_f32 v38, v38, v34, v17
	v_cndmask_b32_e64 v42, v226, v19, s[48:49]
	v_mul_f32_e32 v19, 0x3fb8aa3b, v21
	v_cndmask_b32_e64 v12, v226, v11, s[36:37]
	v_mul_f32_e32 v11, 0x3fb8aa3b, v48
	v_max3_f32 v38, v38, v16, v15
	v_cndmask_b32_e64 v43, v226, v19, s[42:43]
	v_mul_f32_e32 v19, 0x3fb8aa3b, v22
	v_cndmask_b32_e64 v11, v226, v11, s[36:37]
	v_max3_f32 v38, v38, v14, v13
	v_mul_f32_e32 v39, 0x3fb8aa3b, v49
	v_mul_f32_e32 v18, 0x3fb8aa3b, v18
	v_cndmask_b32_e64 v40, v226, v19, s[44:45]
	v_mul_f32_e32 v19, 0x3fb8aa3b, v23
	v_max3_f32 v38, v38, v12, v11
	v_cndmask_b32_e64 v46, v226, v39, s[36:37]
	v_cndmask_b32_e64 v44, v226, v18, s[50:51]
	v_cndmask_b32_e64 v41, v226, v19, s[38:39]
	v_mul_f32_e32 v19, 0x3fb8aa3b, v24
	v_max3_f32 v18, v38, v46, v44
	v_cndmask_b32_e64 v38, v226, v19, s[40:41]
	v_mul_f32_e32 v19, 0x3fb8aa3b, v25
	v_cndmask_b32_e64 v39, v226, v19, s[30:31]
	v_mul_f32_e32 v19, 0x3fb8aa3b, v26
	v_max3_f32 v18, v18, v45, v42
	v_cndmask_b32_e64 v24, v226, v19, s[34:35]
	v_mul_f32_e32 v19, 0x3fb8aa3b, v27
	v_max3_f32 v18, v18, v43, v40
	v_cndmask_b32_e64 v25, v226, v19, s[26:27]
	v_mul_f32_e32 v19, 0x3fb8aa3b, v28
	v_max3_f32 v18, v18, v41, v38
	v_cndmask_b32_e64 v22, v226, v19, s[28:29]
	v_mul_f32_e32 v19, 0x3fb8aa3b, v29
	v_max3_f32 v18, v18, v39, v24
	v_cndmask_b32_e64 v23, v226, v19, s[22:23]
	v_mul_f32_e32 v19, 0x3fb8aa3b, v30
	v_max3_f32 v18, v18, v25, v22
	v_cndmask_b32_e64 v20, v226, v19, s[24:25]
	v_max3_f32 v19, v18, v23, v20
	v_mul_f32_e32 v18, 0x3fb8aa3b, v31
	v_cndmask_b32_e64 v21, v226, v18, s[18:19]
	v_mul_f32_e32 v18, 0x3fb8aa3b, v32
	v_cndmask_b32_e64 v18, v226, v18, s[20:21]
	v_max3_f32 v26, v19, v21, v18
	v_mul_f32_e32 v19, 0x3fb8aa3b, v33
	v_cndmask_b32_e32 v19, v226, v19, vcc
	v_mul_f32_e32 v27, 0x3fb8aa3b, v2
	v_max3_f32 v26, v26, v19, v27
	v_mul_f32_e32 v27, 0x3fb8aa3b, v3
	v_mul_f32_e32 v28, 0x3fb8aa3b, v4
	v_max3_f32 v26, v26, v27, v28
	v_mul_f32_e32 v27, 0x3fb8aa3b, v5
	v_mul_f32_e32 v28, 0x3fb8aa3b, v6
	v_max3_f32 v26, v26, v27, v28
	v_mul_f32_e32 v27, 0x3fb8aa3b, v7
	v_mul_f32_e32 v28, 0x3fb8aa3b, v8
	v_max3_f32 v26, v26, v27, v28
	v_mul_f32_e32 v27, 0x3fb8aa3b, v9
	v_and_b32_e32 v28, 64, v232
	v_max3_f32 v26, v26, v27, s1
	v_xor_b32_e32 v27, 32, v232
	v_add_u32_e32 v28, 64, v28
	v_cmp_lt_i32_e32 vcc, v27, v28
	s_mov_b64 s[18:19], 0
	s_nop 0
	v_cndmask_b32_e32 v27, v232, v27, vcc
	v_lshlrev_b32_e32 v27, 2, v27
	ds_bpermute_b32 v28, v27, v26
	s_waitcnt lgkmcnt(0)
	v_max_f32_e32 v28, v28, v28
	v_max_f32_e32 v26, v26, v28
	v_sub_f32_e32 v10, v10, v26
	v_exp_f32_e32 v10, v10
	v_sub_f32_e32 v29, v144, v26
	v_exp_f32_e32 v29, v29
	v_sub_f32_e32 v30, v142, v26
	v_exp_f32_e32 v30, v30
	v_sub_f32_e32 v31, v143, v26
	v_exp_f32_e32 v31, v31
	v_sub_f32_e32 v32, v140, v26
	v_add_f32_e32 v28, 0, v10
	v_exp_f32_e32 v32, v32
	v_sub_f32_e32 v33, v141, v26
	v_add_f32_e32 v28, v28, v29
	v_exp_f32_e32 v33, v33
	v_sub_f32_e32 v47, v138, v26
	v_add_f32_e32 v28, v28, v30
	v_exp_f32_e32 v47, v47
	v_sub_f32_e32 v48, v139, v26
	v_add_f32_e32 v28, v28, v31
	v_exp_f32_e32 v48, v48
	v_sub_f32_e32 v49, v136, v26
	v_add_f32_e32 v28, v28, v32
	v_exp_f32_e32 v49, v49
	v_sub_f32_e32 v60, v137, v26
	v_add_f32_e32 v28, v28, v33
	v_exp_f32_e32 v60, v60
	v_sub_f32_e32 v61, v134, v26
	v_add_f32_e32 v28, v28, v47
	v_exp_f32_e32 v61, v61
	v_sub_f32_e32 v62, v135, v26
	v_add_f32_e32 v28, v28, v48
	v_exp_f32_e32 v62, v62
	v_sub_f32_e32 v63, v132, v26
	v_add_f32_e32 v28, v28, v49
	v_exp_f32_e32 v63, v63
	v_sub_f32_e32 v64, v133, v26
	v_add_f32_e32 v28, v28, v60
	v_exp_f32_e32 v64, v64
	v_sub_f32_e32 v65, v95, v26
	v_add_f32_e32 v28, v28, v61
	v_exp_f32_e32 v65, v65
	v_sub_f32_e32 v79, v96, v26
	v_add_f32_e32 v28, v28, v62
	v_exp_f32_e32 v79, v79
	v_sub_f32_e32 v80, v94, v26
	v_add_f32_e32 v28, v28, v63
	v_exp_f32_e32 v80, v80
	v_sub_f32_e32 v81, v93, v26
	v_add_f32_e32 v28, v28, v64
	v_exp_f32_e32 v81, v81
	v_sub_f32_e32 v92, v92, v26
	v_add_f32_e32 v28, v28, v65
	v_exp_f32_e32 v92, v92
	v_sub_f32_e32 v91, v91, v26
	v_add_f32_e32 v28, v28, v79
	v_exp_f32_e32 v91, v91
	v_sub_f32_e32 v90, v90, v26
	v_add_f32_e32 v28, v28, v80
	v_exp_f32_e32 v90, v90
	v_sub_f32_e32 v89, v89, v26
	v_add_f32_e32 v28, v28, v81
	v_exp_f32_e32 v89, v89
	v_sub_f32_e32 v88, v88, v26
	v_add_f32_e32 v28, v28, v92
	v_exp_f32_e32 v88, v88
	v_sub_f32_e32 v87, v87, v26
	v_add_f32_e32 v28, v28, v91
	v_exp_f32_e32 v87, v87
	v_sub_f32_e32 v86, v86, v26
	v_add_f32_e32 v28, v28, v90
	v_exp_f32_e32 v86, v86
	v_sub_f32_e32 v85, v85, v26
	v_add_f32_e32 v28, v28, v89
	v_exp_f32_e32 v85, v85
	v_sub_f32_e32 v84, v84, v26
	v_add_f32_e32 v28, v28, v88
	v_exp_f32_e32 v84, v84
	v_sub_f32_e32 v83, v83, v26
	v_add_f32_e32 v28, v28, v87
	v_exp_f32_e32 v83, v83
	v_sub_f32_e32 v82, v82, v26
	v_add_f32_e32 v28, v28, v86
	v_exp_f32_e32 v82, v82
	v_sub_f32_e32 v78, v78, v26
	v_add_f32_e32 v28, v28, v85
	v_exp_f32_e32 v78, v78
	v_sub_f32_e32 v77, v77, v26
	v_add_f32_e32 v28, v28, v84
	v_exp_f32_e32 v77, v77
	v_sub_f32_e32 v76, v76, v26
	v_add_f32_e32 v28, v28, v83
	v_exp_f32_e32 v76, v76
	v_sub_f32_e32 v75, v75, v26
	v_add_f32_e32 v28, v28, v82
	v_exp_f32_e32 v75, v75
	v_sub_f32_e32 v74, v74, v26
	v_add_f32_e32 v28, v28, v78
	v_exp_f32_e32 v74, v74
	v_sub_f32_e32 v73, v73, v26
	v_add_f32_e32 v28, v28, v77
	v_exp_f32_e32 v73, v73
	v_sub_f32_e32 v72, v72, v26
	v_add_f32_e32 v28, v28, v76
	v_exp_f32_e32 v72, v72
	v_sub_f32_e32 v71, v71, v26
	v_add_f32_e32 v28, v28, v75
	v_exp_f32_e32 v71, v71
	v_sub_f32_e32 v70, v70, v26
	v_add_f32_e32 v28, v28, v74
	v_exp_f32_e32 v70, v70
	v_sub_f32_e32 v69, v69, v26
	v_add_f32_e32 v28, v28, v73
	v_exp_f32_e32 v69, v69
	v_sub_f32_e32 v68, v68, v26
	v_add_f32_e32 v28, v28, v72
	v_exp_f32_e32 v68, v68
	v_sub_f32_e32 v67, v67, v26
	v_add_f32_e32 v28, v28, v71
	v_exp_f32_e32 v67, v67
	v_sub_f32_e32 v66, v66, v26
	v_add_f32_e32 v28, v28, v70
	v_exp_f32_e32 v66, v66
	v_sub_f32_e32 v59, v59, v26
	v_add_f32_e32 v28, v28, v69
	v_exp_f32_e32 v59, v59
	v_sub_f32_e32 v58, v58, v26
	v_add_f32_e32 v28, v28, v68
	v_exp_f32_e32 v58, v58
	v_sub_f32_e32 v57, v57, v26
	v_add_f32_e32 v28, v28, v67
	v_exp_f32_e32 v57, v57
	v_sub_f32_e32 v56, v56, v26
	v_add_f32_e32 v28, v28, v66
	v_exp_f32_e32 v56, v56
	v_sub_f32_e32 v55, v55, v26
	v_add_f32_e32 v28, v28, v59
	v_exp_f32_e32 v55, v55
	v_sub_f32_e32 v54, v54, v26
	v_add_f32_e32 v28, v28, v58
	v_exp_f32_e32 v54, v54
	v_sub_f32_e32 v53, v53, v26
	v_add_f32_e32 v28, v28, v57
	v_exp_f32_e32 v53, v53
	v_sub_f32_e32 v52, v52, v26
	v_add_f32_e32 v28, v28, v56
	v_exp_f32_e32 v52, v52
	v_sub_f32_e32 v51, v51, v26
	v_add_f32_e32 v28, v28, v55
	v_exp_f32_e32 v51, v51
	v_sub_f32_e32 v50, v50, v26
	v_add_f32_e32 v28, v28, v54
	v_exp_f32_e32 v50, v50
	v_sub_f32_e32 v37, v37, v26
	v_add_f32_e32 v28, v28, v53
	v_exp_f32_e32 v93, v37
	v_sub_f32_e32 v36, v36, v26
	v_add_f32_e32 v28, v28, v52
	v_exp_f32_e32 v94, v36
	v_sub_f32_e32 v35, v35, v26
	v_add_f32_e32 v28, v28, v51
	v_exp_f32_e32 v95, v35
	v_sub_f32_e32 v34, v34, v26
	v_add_f32_e32 v28, v28, v50
	v_exp_f32_e32 v96, v34
	v_sub_f32_e32 v17, v17, v26
	v_add_f32_e32 v28, v28, v93
	v_exp_f32_e32 v97, v17
	v_sub_f32_e32 v16, v16, v26
	v_add_f32_e32 v28, v28, v94
	v_exp_f32_e32 v132, v16
	v_sub_f32_e32 v15, v15, v26
	v_add_f32_e32 v28, v28, v95
	v_exp_f32_e32 v133, v15
	v_sub_f32_e32 v14, v14, v26
	v_add_f32_e32 v28, v28, v96
	v_exp_f32_e32 v134, v14
	v_sub_f32_e32 v13, v13, v26
	v_add_f32_e32 v17, v28, v97
	v_exp_f32_e32 v135, v13
	v_sub_f32_e32 v12, v12, v26
	v_add_f32_e32 v16, v17, v132
	v_exp_f32_e32 v136, v12
	v_sub_f32_e32 v11, v11, v26
	v_add_f32_e32 v15, v16, v133
	v_exp_f32_e32 v137, v11
	v_add_f32_e32 v14, v15, v134
	v_add_f32_e32 v13, v14, v135
	v_add_f32_e32 v12, v13, v136
	v_add_f32_e32 v11, v12, v137
	v_sub_f32_e32 v12, v46, v26
	v_exp_f32_e32 v46, v12
	v_sub_f32_e32 v12, v44, v26
	v_exp_f32_e32 v138, v12
	v_sub_f32_e32 v12, v45, v26
	v_exp_f32_e32 v139, v12
	v_sub_f32_e32 v12, v42, v26
	v_exp_f32_e32 v140, v12
	v_sub_f32_e32 v12, v43, v26
	v_add_f32_e32 v11, v11, v46
	v_exp_f32_e32 v141, v12
	v_sub_f32_e32 v12, v40, v26
	v_add_f32_e32 v11, v11, v138
	v_exp_f32_e32 v142, v12
	v_sub_f32_e32 v12, v41, v26
	v_add_f32_e32 v11, v11, v139
	v_exp_f32_e32 v143, v12
	v_sub_f32_e32 v12, v38, v26
	v_add_f32_e32 v11, v11, v140
	v_exp_f32_e32 v144, v12
	v_sub_f32_e32 v12, v39, v26
	v_add_f32_e32 v11, v11, v141
	v_exp_f32_e32 v145, v12
	v_sub_f32_e32 v12, v24, v26
	v_add_f32_e32 v11, v11, v142
	v_exp_f32_e32 v146, v12
	v_sub_f32_e32 v12, v25, v26
	v_add_f32_e32 v11, v11, v143
	v_exp_f32_e32 v147, v12
	v_sub_f32_e32 v12, v22, v26
	v_add_f32_e32 v11, v11, v144
	v_exp_f32_e32 v148, v12
	v_sub_f32_e32 v12, v23, v26
	v_add_f32_e32 v11, v11, v145
	v_exp_f32_e32 v149, v12
	v_sub_f32_e32 v12, v20, v26
	v_add_f32_e32 v11, v11, v146
	v_exp_f32_e32 v150, v12
	v_sub_f32_e32 v12, v21, v26
	v_add_f32_e32 v11, v11, v147
	v_exp_f32_e32 v151, v12
	v_sub_f32_e32 v12, v18, v26
	v_add_f32_e32 v11, v11, v148
	v_exp_f32_e32 v152, v12
	v_sub_f32_e32 v12, v19, v26
	v_add_f32_e32 v11, v11, v149
	v_exp_f32_e32 v153, v12
	v_fma_f32 v2, v2, s9, -v26
	v_add_f32_e32 v11, v11, v150
	v_exp_f32_e32 v154, v2
	v_fma_f32 v3, v3, s9, -v26
	v_add_f32_e32 v11, v11, v151
	v_exp_f32_e32 v155, v3
	v_fma_f32 v3, v4, s9, -v26
	v_add_f32_e32 v11, v11, v152
	v_exp_f32_e32 v156, v3
	v_fma_f32 v3, v5, s9, -v26
	v_add_f32_e32 v11, v11, v153
	v_exp_f32_e32 v157, v3
	v_fma_f32 v3, v6, s9, -v26
	v_add_f32_e32 v2, v11, v154
	v_exp_f32_e32 v158, v3
	v_fma_f32 v3, v7, s9, -v26
	v_add_f32_e32 v2, v2, v155
	v_exp_f32_e32 v159, v3
	v_fma_f32 v3, v8, s9, -v26
	v_add_f32_e32 v2, v2, v156
	v_exp_f32_e32 v160, v3
	v_fma_f32 v3, v9, s9, -v26
	v_add_f32_e32 v2, v2, v157
	v_exp_f32_e32 v161, v3
	v_sub_f32_e32 v3, 0xf149f2ca, v26
	v_add_f32_e32 v2, v2, v158
	v_exp_f32_e32 v162, v3
	v_add_f32_e32 v2, v2, v159
	v_add_f32_e32 v2, v2, v160
	v_add_f32_e32 v2, v2, v161
	v_add_f32_e32 v2, v2, v162
	v_add_f32_e32 v2, v2, v162
	v_add_f32_e32 v2, v2, v162
	v_add_f32_e32 v2, v2, v162
	v_add_f32_e32 v2, v2, v162
	v_add_f32_e32 v2, v2, v162
	v_add_f32_e32 v2, v2, v162
	v_add_f32_e32 v163, v2, v162
	v_sub_f32_e32 v2, v201, v26
	v_add_u32_e32 v44, s7, v223
	v_exp_f32_e32 v165, v2
	s_nop 0
	v_cvt_pk_bf16_f32 v2, v10, v29
	s_nop 0
	v_cvt_pk_bf16_f32 v3, v30, v31
	s_nop 0
	v_cvt_pk_bf16_f32 v4, v32, v33
	s_nop 0
	v_cvt_pk_bf16_f32 v5, v47, v48
	ds_read_b64_tr_b16 v[6:7], v44 offset:32256
	ds_read_b64_tr_b16 v[8:9], v44 offset:33408
	ds_read_b64_tr_b16 v[10:11], v44 offset:32320
	ds_read_b64_tr_b16 v[12:13], v44 offset:33472
	ds_bpermute_b32 v164, v27, v163
	s_waitcnt lgkmcnt(3)
	v_mfma_f32_32x32x16_bf16 v[18:33], v[6:9], v[2:5], 0
	s_nop 0
	v_cvt_pk_bf16_f32 v34, v49, v60
	s_nop 0
	v_cvt_pk_bf16_f32 v35, v61, v62
	s_nop 0
	v_cvt_pk_bf16_f32 v36, v63, v64
	s_nop 0
	v_cvt_pk_bf16_f32 v37, v65, v79
	ds_read_b64_tr_b16 v[38:39], v44 offset:34560
	ds_read_b64_tr_b16 v[40:41], v44 offset:35712
	ds_read_b64_tr_b16 v[42:43], v44 offset:34624
	ds_read_b64_tr_b16 v[44:45], v44 offset:35776
	v_add_u32_e32 v47, s6, v223
	s_waitcnt lgkmcnt(5)
	v_mfma_f32_32x32x16_bf16 v[2:17], v[10:13], v[2:5], 0
	s_waitcnt lgkmcnt(2)
	v_mfma_f32_32x32x16_bf16 v[18:33], v[38:41], v[34:37], v[18:33]
	s_waitcnt lgkmcnt(0)
	v_mfma_f32_32x32x16_bf16 v[2:17], v[42:45], v[34:37], v[2:17]
	s_nop 0
	v_cvt_pk_bf16_f32 v34, v80, v81
	s_nop 0
	v_cvt_pk_bf16_f32 v35, v92, v91
	s_nop 0
	v_cvt_pk_bf16_f32 v36, v90, v89
	s_nop 0
	v_cvt_pk_bf16_f32 v37, v88, v87
	ds_read_b64_tr_b16 v[38:39], v47 offset:32256
	ds_read_b64_tr_b16 v[40:41], v47 offset:33408
	ds_read_b64_tr_b16 v[42:43], v47 offset:32320
	ds_read_b64_tr_b16 v[44:45], v47 offset:33472
	s_waitcnt lgkmcnt(2)
	v_mfma_f32_32x32x16_bf16 v[18:33], v[38:41], v[34:37], v[18:33]
	s_waitcnt lgkmcnt(0)
	v_mfma_f32_32x32x16_bf16 v[2:17], v[42:45], v[34:37], v[2:17]
	s_nop 0
	v_cvt_pk_bf16_f32 v34, v86, v85
	s_nop 0
	v_cvt_pk_bf16_f32 v35, v84, v83
	s_nop 0
	v_cvt_pk_bf16_f32 v36, v82, v78
	s_nop 0
	v_cvt_pk_bf16_f32 v37, v77, v76
	ds_read_b64_tr_b16 v[38:39], v47 offset:34560
	ds_read_b64_tr_b16 v[40:41], v47 offset:35712
	ds_read_b64_tr_b16 v[42:43], v47 offset:34624
	ds_read_b64_tr_b16 v[44:45], v47 offset:35776
	v_add_u32_e32 v47, s15, v223
	s_waitcnt lgkmcnt(2)
	v_mfma_f32_32x32x16_bf16 v[18:33], v[38:41], v[34:37], v[18:33]
	s_waitcnt lgkmcnt(0)
	v_mfma_f32_32x32x16_bf16 v[2:17], v[42:45], v[34:37], v[2:17]
	s_nop 0
	v_cvt_pk_bf16_f32 v34, v75, v74
	s_nop 0
	v_cvt_pk_bf16_f32 v35, v73, v72
	s_nop 0
	v_cvt_pk_bf16_f32 v36, v71, v70
	s_nop 0
	v_cvt_pk_bf16_f32 v37, v69, v68
	ds_read_b64_tr_b16 v[38:39], v47 offset:32256
	ds_read_b64_tr_b16 v[40:41], v47 offset:33408
	ds_read_b64_tr_b16 v[42:43], v47 offset:32320
	ds_read_b64_tr_b16 v[44:45], v47 offset:33472
	s_waitcnt lgkmcnt(2)
	v_mfma_f32_32x32x16_bf16 v[18:33], v[38:41], v[34:37], v[18:33]
	s_waitcnt lgkmcnt(0)
	v_mfma_f32_32x32x16_bf16 v[2:17], v[42:45], v[34:37], v[2:17]
	s_nop 0
	v_cvt_pk_bf16_f32 v34, v67, v66
	s_nop 0
	v_cvt_pk_bf16_f32 v35, v59, v58
	s_nop 0
	v_cvt_pk_bf16_f32 v36, v57, v56
	s_nop 0
	v_cvt_pk_bf16_f32 v37, v55, v54
	ds_read_b64_tr_b16 v[38:39], v47 offset:34560
	ds_read_b64_tr_b16 v[40:41], v47 offset:35712
	ds_read_b64_tr_b16 v[42:43], v47 offset:34624
	ds_read_b64_tr_b16 v[44:45], v47 offset:35776
	v_add_u32_e32 v47, s14, v223
	s_waitcnt lgkmcnt(2)
	v_mfma_f32_32x32x16_bf16 v[18:33], v[38:41], v[34:37], v[18:33]
	s_waitcnt lgkmcnt(0)
	v_mfma_f32_32x32x16_bf16 v[2:17], v[42:45], v[34:37], v[2:17]
	s_nop 0
	v_cvt_pk_bf16_f32 v34, v53, v52
	s_nop 0
	v_cvt_pk_bf16_f32 v35, v51, v50
	s_nop 0
	v_cvt_pk_bf16_f32 v36, v93, v94
	s_nop 0
	v_cvt_pk_bf16_f32 v37, v95, v96
	ds_read_b64_tr_b16 v[38:39], v47 offset:32256
	ds_read_b64_tr_b16 v[40:41], v47 offset:33408
	ds_read_b64_tr_b16 v[42:43], v47 offset:32320
	ds_read_b64_tr_b16 v[44:45], v47 offset:33472
	s_waitcnt lgkmcnt(2)
	v_mfma_f32_32x32x16_bf16 v[18:33], v[38:41], v[34:37], v[18:33]
	s_waitcnt lgkmcnt(0)
	v_mfma_f32_32x32x16_bf16 v[2:17], v[42:45], v[34:37], v[2:17]
	s_nop 0
	v_cvt_pk_bf16_f32 v34, v97, v132
	s_nop 0
	v_cvt_pk_bf16_f32 v35, v133, v134
	s_nop 0
	v_cvt_pk_bf16_f32 v36, v135, v136
	s_nop 0
	v_cvt_pk_bf16_f32 v37, v137, v46
	ds_read_b64_tr_b16 v[38:39], v47 offset:34560
	ds_read_b64_tr_b16 v[40:41], v47 offset:35712
	ds_read_b64_tr_b16 v[42:43], v47 offset:34624
	ds_read_b64_tr_b16 v[44:45], v47 offset:35776
	v_add_u32_e32 v46, s0, v223
	s_waitcnt lgkmcnt(2)
	v_mfma_f32_32x32x16_bf16 v[18:33], v[38:41], v[34:37], v[18:33]
	s_waitcnt lgkmcnt(0)
	v_mfma_f32_32x32x16_bf16 v[2:17], v[42:45], v[34:37], v[2:17]
	s_nop 0
	v_cvt_pk_bf16_f32 v34, v138, v139
	s_nop 0
	v_cvt_pk_bf16_f32 v35, v140, v141
	s_nop 0
	v_cvt_pk_bf16_f32 v36, v142, v143
	s_nop 0
	v_cvt_pk_bf16_f32 v37, v144, v145
	ds_read_b64_tr_b16 v[38:39], v46 offset:32256
	ds_read_b64_tr_b16 v[40:41], v46 offset:33408
	ds_read_b64_tr_b16 v[42:43], v46 offset:32320
	ds_read_b64_tr_b16 v[44:45], v46 offset:33472
	s_waitcnt lgkmcnt(2)
	v_mfma_f32_32x32x16_bf16 v[18:33], v[38:41], v[34:37], v[18:33]
	s_waitcnt lgkmcnt(0)
	v_mfma_f32_32x32x16_bf16 v[2:17], v[42:45], v[34:37], v[2:17]
	s_nop 0
	v_cvt_pk_bf16_f32 v34, v146, v147
	s_nop 0
	v_cvt_pk_bf16_f32 v35, v148, v149
	s_nop 0
	v_cvt_pk_bf16_f32 v36, v150, v151
	s_nop 0
	v_cvt_pk_bf16_f32 v37, v152, v153
	ds_read_b64_tr_b16 v[38:39], v46 offset:34560
	ds_read_b64_tr_b16 v[40:41], v46 offset:35712
	ds_read_b64_tr_b16 v[42:43], v46 offset:34624
	ds_read_b64_tr_b16 v[44:45], v46 offset:35776
	s_waitcnt lgkmcnt(2)
	v_mfma_f32_32x32x16_bf16 v[18:33], v[38:41], v[34:37], v[18:33]
	s_waitcnt lgkmcnt(0)
	v_mfma_f32_32x32x16_bf16 v[2:17], v[42:45], v[34:37], v[2:17]
	s_nop 0
	v_cvt_pk_bf16_f32 v34, v154, v155
	s_nop 0
	v_cvt_pk_bf16_f32 v35, v156, v157
	s_nop 0
	v_cvt_pk_bf16_f32 v36, v158, v159
	s_nop 0
	v_cvt_pk_bf16_f32 v37, v160, v161
	ds_read_b64_tr_b16 v[38:39], v223 offset:59904
	ds_read_b64_tr_b16 v[40:41], v223 offset:61056
	ds_read_b64_tr_b16 v[42:43], v223 offset:59968
	ds_read_b64_tr_b16 v[44:45], v223 offset:61120
	s_waitcnt lgkmcnt(2)
	v_mfma_f32_32x32x16_bf16 v[18:33], v[38:41], v[34:37], v[18:33]
	s_waitcnt lgkmcnt(0)
	v_mfma_f32_32x32x16_bf16 v[2:17], v[42:45], v[34:37], v[2:17]
	s_nop 0
	v_cvt_pk_bf16_f32 v34, v162, v162
	s_nop 0
	v_cvt_pk_bf16_f32 v35, v162, v162
	s_nop 0
	v_cvt_pk_bf16_f32 v36, v162, v162
	s_nop 0
	v_cvt_pk_bf16_f32 v37, v162, v162
	ds_read_b64_tr_b16 v[38:39], v223 offset:62208
	ds_read_b64_tr_b16 v[40:41], v223 offset:63360
	ds_read_b64_tr_b16 v[42:43], v223 offset:62272
	ds_read_b64_tr_b16 v[44:45], v223 offset:63424
	s_waitcnt lgkmcnt(2)
	v_mfma_f32_32x32x16_bf16 v[18:33], v[38:41], v[34:37], v[18:33]
	s_waitcnt lgkmcnt(0)
	v_mfma_f32_32x32x16_bf16 v[2:17], v[42:45], v[34:37], v[2:17]
	v_add_f32_e32 v34, v163, v164
	v_add_f32_e32 v34, v165, v34
	v_div_scale_f32 v35, s[0:1], v34, v34, 1.0
	v_rcp_f32_e32 v36, v35
	s_nop 0
	v_fma_f32 v37, -v35, v36, 1.0
	v_fmac_f32_e32 v36, v37, v36
	v_div_scale_f32 v37, vcc, 1.0, v34, 1.0
	v_mul_f32_e32 v38, v37, v36
	v_fma_f32 v39, -v35, v38, v37
	v_fmac_f32_e32 v38, v39, v36
	v_fma_f32 v35, -v35, v38, v37
	v_div_fmas_f32 v35, v35, v36, v38
	v_div_fixup_f32 v36, v35, v34, 1.0
	v_mul_f32_e32 v36, 0x42c80000, v36
	v_mul_f32_e32 v3, v36, v3
	v_mul_f32_e32 v2, v36, v2
	v_mul_f32_e32 v4, v36, v4
	v_mul_f32_e32 v5, v36, v5
	v_med3_f32 v3, v3, s13, v227
	v_med3_f32 v2, v2, s13, v227
	v_rndne_f32_e32 v3, v3
	v_med3_f32 v4, v4, s13, v227
	v_med3_f32 v5, v5, s13, v227
	v_rndne_f32_e32 v2, v2
	v_cvt_i32_f32_e32 v3, v3
	v_rndne_f32_e32 v4, v4
	v_rndne_f32_e32 v5, v5
	v_cvt_i32_f32_e32 v2, v2
	v_cvt_i32_f32_sdwa v4, v4 dst_sel:WORD_1 dst_unused:UNUSED_PAD src0_sel:DWORD
	v_cvt_i32_f32_e32 v5, v5
	v_lshlrev_b32_e32 v3, 8, v3
	v_and_b32_e32 v3, 0xff00, v3
	v_and_b32_e32 v4, 0xff0000, v4
	v_perm_b32 v2, v5, v2, s33
	v_lshl_add_u64 v[34:35], v[214:215], 0, v[216:217]
	v_or3_b32 v2, v2, v3, v4
	v_mul_f32_e32 v3, v36, v23
	global_store_dword v[34:35], v2, off offset:32
	v_mul_f32_e32 v2, v36, v22
	v_mul_f32_e32 v4, v36, v24
	v_mul_f32_e32 v5, v36, v25
	v_med3_f32 v3, v3, s13, v227
	v_med3_f32 v2, v2, s13, v227
	v_rndne_f32_e32 v3, v3
	v_med3_f32 v4, v4, s13, v227
	v_med3_f32 v5, v5, s13, v227
	v_rndne_f32_e32 v2, v2
	v_cvt_i32_f32_e32 v3, v3
	v_rndne_f32_e32 v4, v4
	v_rndne_f32_e32 v5, v5
	v_cvt_i32_f32_e32 v2, v2
	v_cvt_i32_f32_sdwa v4, v4 dst_sel:WORD_1 dst_unused:UNUSED_PAD src0_sel:DWORD
	v_cvt_i32_f32_e32 v5, v5
	v_lshlrev_b32_e32 v3, 8, v3
	v_and_b32_e32 v3, 0xff00, v3
	v_and_b32_e32 v4, 0xff0000, v4
	v_perm_b32 v2, v5, v2, s33
	v_or3_b32 v2, v2, v3, v4
	v_mul_f32_e32 v3, v36, v7
	global_store_dword v[34:35], v2, off offset:8
	v_mul_f32_e32 v2, v36, v6
	v_mul_f32_e32 v4, v36, v8
	v_mul_f32_e32 v5, v36, v9
	v_med3_f32 v3, v3, s13, v227
	v_med3_f32 v2, v2, s13, v227
	v_rndne_f32_e32 v3, v3
	v_med3_f32 v4, v4, s13, v227
	v_med3_f32 v5, v5, s13, v227
	v_rndne_f32_e32 v2, v2
	v_cvt_i32_f32_e32 v3, v3
	v_rndne_f32_e32 v4, v4
	v_rndne_f32_e32 v5, v5
	v_cvt_i32_f32_e32 v2, v2
	v_cvt_i32_f32_sdwa v4, v4 dst_sel:WORD_1 dst_unused:UNUSED_PAD src0_sel:DWORD
	v_cvt_i32_f32_e32 v5, v5
	v_lshlrev_b32_e32 v3, 8, v3
	v_and_b32_e32 v3, 0xff00, v3
	v_and_b32_e32 v4, 0xff0000, v4
	v_perm_b32 v2, v5, v2, s33
	v_or3_b32 v2, v2, v3, v4
	v_mul_f32_e32 v3, v36, v27
	global_store_dword v[34:35], v2, off offset:40
	v_mul_f32_e32 v2, v36, v26
	v_mul_f32_e32 v4, v36, v28
	v_mul_f32_e32 v5, v36, v29
	v_med3_f32 v3, v3, s13, v227
	v_med3_f32 v2, v2, s13, v227
	v_rndne_f32_e32 v3, v3
	v_med3_f32 v4, v4, s13, v227
	v_med3_f32 v5, v5, s13, v227
	v_rndne_f32_e32 v2, v2
	v_cvt_i32_f32_e32 v3, v3
	v_rndne_f32_e32 v4, v4
	v_rndne_f32_e32 v5, v5
	v_cvt_i32_f32_e32 v2, v2
	v_cvt_i32_f32_sdwa v4, v4 dst_sel:WORD_1 dst_unused:UNUSED_PAD src0_sel:DWORD
	v_cvt_i32_f32_e32 v5, v5
	v_lshlrev_b32_e32 v3, 8, v3
	v_and_b32_e32 v3, 0xff00, v3
	v_and_b32_e32 v4, 0xff0000, v4
	v_perm_b32 v2, v5, v2, s33
	v_or3_b32 v2, v2, v3, v4
	v_mul_f32_e32 v3, v36, v11
	global_store_dword v[34:35], v2, off offset:16
	v_mul_f32_e32 v2, v36, v10
	v_mul_f32_e32 v4, v36, v12
	v_mul_f32_e32 v5, v36, v13
	v_med3_f32 v3, v3, s13, v227
	v_med3_f32 v2, v2, s13, v227
	v_rndne_f32_e32 v3, v3
	v_med3_f32 v4, v4, s13, v227
	v_med3_f32 v5, v5, s13, v227
	v_rndne_f32_e32 v2, v2
	v_cvt_i32_f32_e32 v3, v3
	v_rndne_f32_e32 v4, v4
	v_rndne_f32_e32 v5, v5
	v_cvt_i32_f32_e32 v2, v2
	v_cvt_i32_f32_sdwa v4, v4 dst_sel:WORD_1 dst_unused:UNUSED_PAD src0_sel:DWORD
	v_cvt_i32_f32_e32 v5, v5
	v_lshlrev_b32_e32 v3, 8, v3
	v_and_b32_e32 v3, 0xff00, v3
	v_and_b32_e32 v4, 0xff0000, v4
	v_perm_b32 v2, v5, v2, s33
	v_or3_b32 v2, v2, v3, v4
	v_mul_f32_e32 v3, v36, v31
	global_store_dword v[34:35], v2, off offset:48
	v_mul_f32_e32 v2, v36, v30
	v_mul_f32_e32 v4, v36, v32
	v_mul_f32_e32 v5, v36, v33
	v_med3_f32 v3, v3, s13, v227
	v_med3_f32 v2, v2, s13, v227
	v_rndne_f32_e32 v3, v3
	v_med3_f32 v4, v4, s13, v227
	v_med3_f32 v5, v5, s13, v227
	v_rndne_f32_e32 v2, v2
	v_cvt_i32_f32_e32 v3, v3
	v_rndne_f32_e32 v4, v4
	v_rndne_f32_e32 v5, v5
	v_cvt_i32_f32_e32 v2, v2
	v_cvt_i32_f32_sdwa v4, v4 dst_sel:WORD_1 dst_unused:UNUSED_PAD src0_sel:DWORD
	v_cvt_i32_f32_e32 v5, v5
	v_lshlrev_b32_e32 v3, 8, v3
	v_and_b32_e32 v3, 0xff00, v3
	v_and_b32_e32 v4, 0xff0000, v4
	v_perm_b32 v2, v5, v2, s33
	v_mul_f32_e32 v19, v36, v19
	v_or3_b32 v2, v2, v3, v4
	v_mul_f32_e32 v3, v36, v15
	v_mul_f32_e32 v18, v36, v18
	v_mul_f32_e32 v20, v36, v20
	v_mul_f32_e32 v21, v36, v21
	v_med3_f32 v19, v19, s13, v227
	global_store_dword v[34:35], v2, off offset:24
	v_mul_f32_e32 v2, v36, v14
	v_mul_f32_e32 v4, v36, v16
	v_mul_f32_e32 v5, v36, v17
	v_med3_f32 v3, v3, s13, v227
	v_med3_f32 v18, v18, s13, v227
	v_rndne_f32_e32 v19, v19
	v_med3_f32 v20, v20, s13, v227
	v_med3_f32 v21, v21, s13, v227
	v_med3_f32 v2, v2, s13, v227
	v_rndne_f32_e32 v3, v3
	v_med3_f32 v4, v4, s13, v227
	v_med3_f32 v5, v5, s13, v227
	v_rndne_f32_e32 v18, v18
	v_cvt_i32_f32_e32 v19, v19
	v_rndne_f32_e32 v20, v20
	v_rndne_f32_e32 v21, v21
	v_rndne_f32_e32 v2, v2
	v_cvt_i32_f32_e32 v3, v3
	v_rndne_f32_e32 v4, v4
	v_rndne_f32_e32 v5, v5
	v_cvt_i32_f32_e32 v18, v18
	v_cvt_i32_f32_sdwa v20, v20 dst_sel:WORD_1 dst_unused:UNUSED_PAD src0_sel:DWORD
	v_cvt_i32_f32_e32 v21, v21
	v_cvt_i32_f32_e32 v2, v2
	v_cvt_i32_f32_sdwa v4, v4 dst_sel:WORD_1 dst_unused:UNUSED_PAD src0_sel:DWORD
	v_cvt_i32_f32_e32 v5, v5
	v_lshlrev_b32_e32 v19, 8, v19
	v_lshlrev_b32_e32 v3, 8, v3
	v_and_b32_e32 v19, 0xff00, v19
	v_and_b32_e32 v20, 0xff0000, v20
	v_perm_b32 v18, v21, v18, s33
	v_and_b32_e32 v3, 0xff00, v3
	v_and_b32_e32 v4, 0xff0000, v4
	v_perm_b32 v2, v5, v2, s33
	v_or3_b32 v18, v18, v19, v20
	v_or3_b32 v2, v2, v3, v4
	s_and_b64 vcc, exec, s[16:17]
	s_mov_b32 s16, 1
	global_store_dword v[34:35], v18, off
	global_store_dword v[34:35], v2, off offset:56
	v_readlane_b32 s0, v254, 60
	v_readlane_b32 s96, v254, 45
	v_readlane_b32 s1, v254, 61
	v_readlane_b32 s97, v254, 46
	s_mov_b64 s[2:3], -1
	s_and_b64 vcc, exec, s[0:1]
	v_readlane_b32 s97, v253, 28
	v_readlane_b32 s16, v254, 18
	v_readlane_b32 s60, v253, 12
	s_barrier
	v_readlane_b32 s17, v254, 19
	v_readlane_b32 s18, v254, 20
	v_readlane_b32 s19, v254, 21
	v_readlane_b32 s20, v254, 22
	v_readlane_b32 s21, v254, 23
	v_readlane_b32 s22, v254, 24
	v_readlane_b32 s23, v254, 25
	v_readlane_b32 s24, v254, 26
	v_readlane_b32 s25, v254, 27
	v_readlane_b32 s26, v254, 28
	v_readlane_b32 s27, v254, 29
	v_readlane_b32 s28, v254, 30
	v_readlane_b32 s29, v254, 31
	v_readlane_b32 s30, v254, 32
	v_readlane_b32 s31, v254, 33
	v_readlane_b32 s61, v253, 13
	s_cbranch_vccz .LBB0_627
	ds_write_b128 v233, v[106:109]
	ds_write_b128 v233, v[102:105] offset:32256
	ds_write_b128 v225, v[98:101]
	ds_write_b128 v225, v[110:113] offset:32256
	s_mov_b64 s[2:3], exec
	v_readlane_b32 s0, v253, 18
	v_readlane_b32 s1, v253, 19
	s_and_b64 s[0:1], s[2:3], s[0:1]
	s_mov_b64 exec, s[0:1]
	s_cbranch_execz .LBB0_649
	ds_write_b128 v233, v[114:117] offset:18432
	ds_write_b128 v233, v[118:121] offset:50688
